# KV V^T tiles 24..39 moved from P4 into idle last-round slots of P1; 64-chunk state scan with 16 chunks in flight per batch (no KVRELOC, seam 9 global)
# baseline (speedup 1.0000x reference)
.LBB0_453:
	v_readlane_b32 s4, v244, 47
	v_readlane_b32 s5, v244, 48
	s_cmp_gt_i32 s5, 2
	s_cselect_b64 s[0:1], -1, 0
	s_and_b64 s[2:3], s[2:3], s[0:1]
	s_andn2_b64 vcc, exec, s[2:3]
	v_readlane_b32 s6, v244, 49
	v_readlane_b32 s7, v244, 50
	s_cbranch_vccnz .LBB0_507
	v_readlane_b32 s85, v244, 51
	s_sub_u32 s85, s85, 0xc0
	s_cmp_lt_u32 s85, 16
	s_cbranch_scc0 .Lkvp1_skip
	s_add_u32 s85, s85, 24
	s_mov_b32 s84, 1
	s_mov_b64 s[90:91], s[20:21]
	s_mov_b64 s[92:93], s[22:23]
	s_branch .Lkvp1_entry
.Lkvp1_ret:
	s_mov_b32 s84, 0
	s_mov_b64 s[20:21], s[90:91]
	s_mov_b64 s[22:23], s[92:93]
	v_readlane_b32 s4, v244, 47
	v_readlane_b32 s5, v244, 48
	v_readlane_b32 s6, v244, 49
	v_readlane_b32 s7, v244, 50
.Lkvp1_skip:
	s_waitcnt vmcnt(0)
	s_waitcnt vmcnt(0)
	s_barrier
	s_mov_b64 s[2:3], exec
	v_readlane_b32 s4, v244, 13
	v_readlane_b32 s5, v244, 14
	s_and_b64 s[4:5], s[2:3], s[4:5]
	s_mov_b64 exec, s[4:5]
	s_cbranch_execz .LBB0_506
	s_add_i32 s4, 0, 0x23fc0
	v_mov_b32_e32 v0, s4
	s_waitcnt vmcnt(0) expcnt(0) lgkmcnt(0)
	ds_read_b32 v2, v0
	s_add_i32 s4, 0, 0x23fc4
	v_mov_b32_e32 v0, s4
	ds_read_b32 v0, v0
	s_waitcnt lgkmcnt(1)
	v_cmp_ne_u32_e32 vcc, 0, v2
	s_cbranch_vccnz .LBB0_470
	v_readlane_b32 s4, v244, 8
	v_readlane_b32 s5, v244, 9
	v_readlane_b32 s36, v244, 0
	s_load_dwordx2 s[8:9], s[4:5], 0x4
	v_readlane_b32 s42, v244, 6
	v_readlane_b32 s43, v244, 7
	s_add_u32 s4, s42, 0x1fd00200
	s_addc_u32 s5, s43, 0
	s_add_u32 s6, s42, 0x1fd00400
	s_addc_u32 s7, s43, 0
	s_waitcnt lgkmcnt(0)
	s_mul_i32 s33, s8, s86
	s_add_u32 s8, s42, 0x1fd00500
	s_mul_i32 s33, s33, s9
	s_addc_u32 s9, s43, 0
	s_add_u32 s10, s42, 0x1fd00600
	s_addc_u32 s11, s43, 0
	s_add_u32 s12, s42, 0x1fd00700
	s_addc_u32 s13, s43, 0
	s_add_u32 s14, s42, 0x1fd00800
	s_addc_u32 s15, s43, 0
	s_add_u32 s16, s42, 0x1fd00900
	s_addc_u32 s17, s43, 0
	s_add_u32 s18, s42, 0x1fd00a00
	s_addc_u32 s19, s43, 0
	s_add_u32 s24, s42, 0x1fd00b00
	s_addc_u32 s25, s43, 0
	s_add_u32 s26, s42, 0x1fd00c00
	s_addc_u32 s27, s43, 0
	s_add_u32 s28, s42, 0x1fd00d00
	s_addc_u32 s29, s43, 0
	s_add_u32 s30, s42, 0x1fd00e00
	s_addc_u32 s31, s43, 0
	s_add_u32 s34, s42, 0x1fd00f00
	s_addc_u32 s35, s43, 0
	v_readlane_b32 s37, v244, 1
	s_add_u32 s36, s42, 0x1fd01000
	v_readlane_b32 s38, v244, 2
	s_addc_u32 s37, s43, 0
	v_readlane_b32 s39, v244, 3
	s_add_u32 s38, s42, 0x1fd01100
	v_readlane_b32 s40, v244, 4
	s_addc_u32 s39, s43, 0
	v_readlane_b32 s41, v244, 5
	s_add_u32 s40, s42, 0x1fd01200
	s_addc_u32 s41, s43, 0
	s_add_u32 s42, s42, 0x1fd01300
	s_addc_u32 s43, s43, 0
	s_mov_b32 s50, 1
	v_mov_b32_e32 v16, 0
	s_branch .LBB0_458

.LBB0_1477:
	s_andn2_saveexec_b64 s[8:9], s[8:9]
	s_cbranch_execz .LBB0_1473
	v_bfe_u32 v0, v33, 10, 1
	v_lshrrev_b32_e32 v1, 14, v33
	v_lshlrev_b32_e32 v1, 6, v1
	v_cmp_ne_u32_e32 vcc, 0, v0
	v_add_u32_e32 v2, 63, v1
	v_cndmask_b32_e32 v1, v1, v2, vcc
	v_bfe_u32 v2, v33, 10, 4
	v_lshl_or_b32 v1, v1, 4, v2
	v_lshlrev_b32_e32 v2, 4, v33
	v_and_b32_e32 v2, 0x3ff0, v2
	v_lshl_add_u32 v2, v1, 14, v2
	v_readlane_b32 s20, v244, 4
	v_readlane_b32 s21, v244, 5
	v_mov_b32_e32 v3, 0
	v_lshl_add_u64 v[4:5], s[20:21], 0, v[2:3]
	v_mov_b32_e32 v6, v4
	v_mov_b32_e32 v7, v5
	v_lshlrev_b32_e32 v2, 2, v1
	v_lshl_add_u64 v[128:129], s[4:5], 0, v[2:3]
	v_mov_b32_e32 v0, 0x40000
	v_mov_b32_e32 v1, 0xfffc0000
	v_cndmask_b32_e32 v130, v0, v1, vcc
	v_cndmask_b32_e64 v131, 0, -1, vcc
	v_mov_b32_e32 v0, 64
	v_mov_b32_e32 v1, 0xffffffc0
	v_cndmask_b32_e32 v132, v0, v1, vcc
	v_mov_b32_e32 v133, v131
	v_mov_b32_e32 v10, 0
	v_mov_b32_e32 v11, 0
	v_mov_b32_e32 v12, 0
	v_mov_b32_e32 v13, 0
	v_mov_b32_e32 v14, 0
	v_mov_b32_e32 v15, 0
	v_mov_b32_e32 v16, 0
	v_mov_b32_e32 v17, 0
	s_mov_b32 s13, 0
.Lscan16_loop:
	global_load_dword v146, v[128:129], off
	v_lshl_add_u64 v[128:129], v[128:129], 0, v[132:133]
	global_load_dword v148, v[128:129], off
	v_lshl_add_u64 v[128:129], v[128:129], 0, v[132:133]
	global_load_dword v150, v[128:129], off
	v_lshl_add_u64 v[128:129], v[128:129], 0, v[132:133]
	global_load_dword v152, v[128:129], off
	v_lshl_add_u64 v[128:129], v[128:129], 0, v[132:133]
	global_load_dword v154, v[128:129], off
	v_lshl_add_u64 v[128:129], v[128:129], 0, v[132:133]
	global_load_dword v156, v[128:129], off
	v_lshl_add_u64 v[128:129], v[128:129], 0, v[132:133]
	global_load_dword v158, v[128:129], off
	v_lshl_add_u64 v[128:129], v[128:129], 0, v[132:133]
	global_load_dword v160, v[128:129], off
	v_lshl_add_u64 v[128:129], v[128:129], 0, v[132:133]
	global_load_dword v162, v[128:129], off
	v_lshl_add_u64 v[128:129], v[128:129], 0, v[132:133]
	global_load_dword v164, v[128:129], off
	v_lshl_add_u64 v[128:129], v[128:129], 0, v[132:133]
	global_load_dword v166, v[128:129], off
	v_lshl_add_u64 v[128:129], v[128:129], 0, v[132:133]
	global_load_dword v100, v[128:129], off
	v_lshl_add_u64 v[128:129], v[128:129], 0, v[132:133]
	global_load_dword v102, v[128:129], off
	v_lshl_add_u64 v[128:129], v[128:129], 0, v[132:133]
	global_load_dword v104, v[128:129], off
	v_lshl_add_u64 v[128:129], v[128:129], 0, v[132:133]
	global_load_dword v106, v[128:129], off
	v_lshl_add_u64 v[128:129], v[128:129], 0, v[132:133]
	global_load_dword v108, v[128:129], off
	v_lshl_add_u64 v[128:129], v[128:129], 0, v[132:133]
	global_load_dwordx4 v[36:39], v[4:5], off
	v_lshl_add_u64 v[4:5], v[4:5], 0, v[130:131]
	global_load_dwordx4 v[40:43], v[4:5], off
	v_lshl_add_u64 v[4:5], v[4:5], 0, v[130:131]
	global_load_dwordx4 v[44:47], v[4:5], off
	v_lshl_add_u64 v[4:5], v[4:5], 0, v[130:131]
	global_load_dwordx4 v[48:51], v[4:5], off
	v_lshl_add_u64 v[4:5], v[4:5], 0, v[130:131]
	global_load_dwordx4 v[52:55], v[4:5], off
	v_lshl_add_u64 v[4:5], v[4:5], 0, v[130:131]
	global_load_dwordx4 v[56:59], v[4:5], off
	v_lshl_add_u64 v[4:5], v[4:5], 0, v[130:131]
	global_load_dwordx4 v[60:63], v[4:5], off
	v_lshl_add_u64 v[4:5], v[4:5], 0, v[130:131]
	global_load_dwordx4 v[64:67], v[4:5], off
	v_lshl_add_u64 v[4:5], v[4:5], 0, v[130:131]
	global_load_dwordx4 v[68:71], v[4:5], off
	v_lshl_add_u64 v[4:5], v[4:5], 0, v[130:131]
	global_load_dwordx4 v[72:75], v[4:5], off
	v_lshl_add_u64 v[4:5], v[4:5], 0, v[130:131]
	global_load_dwordx4 v[76:79], v[4:5], off
	v_lshl_add_u64 v[4:5], v[4:5], 0, v[130:131]
	global_load_dwordx4 v[80:83], v[4:5], off
	v_lshl_add_u64 v[4:5], v[4:5], 0, v[130:131]
	global_load_dwordx4 v[84:87], v[4:5], off
	v_lshl_add_u64 v[4:5], v[4:5], 0, v[130:131]
	global_load_dwordx4 v[88:91], v[4:5], off
	v_lshl_add_u64 v[4:5], v[4:5], 0, v[130:131]
	global_load_dwordx4 v[92:95], v[4:5], off
	v_lshl_add_u64 v[4:5], v[4:5], 0, v[130:131]
	global_load_dwordx4 v[96:99], v[4:5], off
	v_lshl_add_u64 v[4:5], v[4:5], 0, v[130:131]
	v_cvt_pk_bf16_f32 v0, v10, v11
	v_cvt_pk_bf16_f32 v1, v12, v13
	v_cvt_pk_bf16_f32 v2, v14, v15
	v_cvt_pk_bf16_f32 v3, v16, v17
	global_store_dwordx4 v[6:7], v[0:3], off
	v_lshl_add_u64 v[6:7], v[6:7], 0, v[130:131]
	s_waitcnt vmcnt(16)
	v_lshlrev_b32_e32 v18, 16, v36
	v_and_b32_e32 v19, 0xffff0000, v36
	v_lshlrev_b32_e32 v20, 16, v37
	v_and_b32_e32 v21, 0xffff0000, v37
	v_lshlrev_b32_e32 v22, 16, v38
	v_and_b32_e32 v23, 0xffff0000, v38
	v_lshlrev_b32_e32 v24, 16, v39
	v_and_b32_e32 v25, 0xffff0000, v39
	v_pk_fma_f32 v[10:11], v[146:147], v[10:11], v[18:19] op_sel_hi:[0,1,1]
	v_pk_fma_f32 v[12:13], v[146:147], v[12:13], v[20:21] op_sel_hi:[0,1,1]
	v_pk_fma_f32 v[14:15], v[146:147], v[14:15], v[22:23] op_sel_hi:[0,1,1]
	v_pk_fma_f32 v[16:17], v[146:147], v[16:17], v[24:25] op_sel_hi:[0,1,1]
	v_cvt_pk_bf16_f32 v0, v10, v11
	v_cvt_pk_bf16_f32 v1, v12, v13
	v_cvt_pk_bf16_f32 v2, v14, v15
	v_cvt_pk_bf16_f32 v3, v16, v17
	global_store_dwordx4 v[6:7], v[0:3], off
	v_lshl_add_u64 v[6:7], v[6:7], 0, v[130:131]
	s_waitcnt vmcnt(16)
	v_lshlrev_b32_e32 v18, 16, v40
	v_and_b32_e32 v19, 0xffff0000, v40
	v_lshlrev_b32_e32 v20, 16, v41
	v_and_b32_e32 v21, 0xffff0000, v41
	v_lshlrev_b32_e32 v22, 16, v42
	v_and_b32_e32 v23, 0xffff0000, v42
	v_lshlrev_b32_e32 v24, 16, v43
	v_and_b32_e32 v25, 0xffff0000, v43
	v_pk_fma_f32 v[10:11], v[148:149], v[10:11], v[18:19] op_sel_hi:[0,1,1]
	v_pk_fma_f32 v[12:13], v[148:149], v[12:13], v[20:21] op_sel_hi:[0,1,1]
	v_pk_fma_f32 v[14:15], v[148:149], v[14:15], v[22:23] op_sel_hi:[0,1,1]
	v_pk_fma_f32 v[16:17], v[148:149], v[16:17], v[24:25] op_sel_hi:[0,1,1]
	v_cvt_pk_bf16_f32 v0, v10, v11
	v_cvt_pk_bf16_f32 v1, v12, v13
	v_cvt_pk_bf16_f32 v2, v14, v15
	v_cvt_pk_bf16_f32 v3, v16, v17
	global_store_dwordx4 v[6:7], v[0:3], off
	v_lshl_add_u64 v[6:7], v[6:7], 0, v[130:131]
	s_waitcnt vmcnt(16)
	v_lshlrev_b32_e32 v18, 16, v44
	v_and_b32_e32 v19, 0xffff0000, v44
	v_lshlrev_b32_e32 v20, 16, v45
	v_and_b32_e32 v21, 0xffff0000, v45
	v_lshlrev_b32_e32 v22, 16, v46
	v_and_b32_e32 v23, 0xffff0000, v46
	v_lshlrev_b32_e32 v24, 16, v47
	v_and_b32_e32 v25, 0xffff0000, v47
	v_pk_fma_f32 v[10:11], v[150:151], v[10:11], v[18:19] op_sel_hi:[0,1,1]
	v_pk_fma_f32 v[12:13], v[150:151], v[12:13], v[20:21] op_sel_hi:[0,1,1]
	v_pk_fma_f32 v[14:15], v[150:151], v[14:15], v[22:23] op_sel_hi:[0,1,1]
	v_pk_fma_f32 v[16:17], v[150:151], v[16:17], v[24:25] op_sel_hi:[0,1,1]
	v_cvt_pk_bf16_f32 v0, v10, v11
	v_cvt_pk_bf16_f32 v1, v12, v13
	v_cvt_pk_bf16_f32 v2, v14, v15
	v_cvt_pk_bf16_f32 v3, v16, v17
	global_store_dwordx4 v[6:7], v[0:3], off
	v_lshl_add_u64 v[6:7], v[6:7], 0, v[130:131]
	s_waitcnt vmcnt(16)
	v_lshlrev_b32_e32 v18, 16, v48
	v_and_b32_e32 v19, 0xffff0000, v48
	v_lshlrev_b32_e32 v20, 16, v49
	v_and_b32_e32 v21, 0xffff0000, v49
	v_lshlrev_b32_e32 v22, 16, v50
	v_and_b32_e32 v23, 0xffff0000, v50
	v_lshlrev_b32_e32 v24, 16, v51
	v_and_b32_e32 v25, 0xffff0000, v51
	v_pk_fma_f32 v[10:11], v[152:153], v[10:11], v[18:19] op_sel_hi:[0,1,1]
	v_pk_fma_f32 v[12:13], v[152:153], v[12:13], v[20:21] op_sel_hi:[0,1,1]
	v_pk_fma_f32 v[14:15], v[152:153], v[14:15], v[22:23] op_sel_hi:[0,1,1]
	v_pk_fma_f32 v[16:17], v[152:153], v[16:17], v[24:25] op_sel_hi:[0,1,1]
	v_cvt_pk_bf16_f32 v0, v10, v11
	v_cvt_pk_bf16_f32 v1, v12, v13
	v_cvt_pk_bf16_f32 v2, v14, v15
	v_cvt_pk_bf16_f32 v3, v16, v17
	global_store_dwordx4 v[6:7], v[0:3], off
	v_lshl_add_u64 v[6:7], v[6:7], 0, v[130:131]
	s_waitcnt vmcnt(16)
	v_lshlrev_b32_e32 v18, 16, v52
	v_and_b32_e32 v19, 0xffff0000, v52
	v_lshlrev_b32_e32 v20, 16, v53
	v_and_b32_e32 v21, 0xffff0000, v53
	v_lshlrev_b32_e32 v22, 16, v54
	v_and_b32_e32 v23, 0xffff0000, v54
	v_lshlrev_b32_e32 v24, 16, v55
	v_and_b32_e32 v25, 0xffff0000, v55
	v_pk_fma_f32 v[10:11], v[154:155], v[10:11], v[18:19] op_sel_hi:[0,1,1]
	v_pk_fma_f32 v[12:13], v[154:155], v[12:13], v[20:21] op_sel_hi:[0,1,1]
	v_pk_fma_f32 v[14:15], v[154:155], v[14:15], v[22:23] op_sel_hi:[0,1,1]
	v_pk_fma_f32 v[16:17], v[154:155], v[16:17], v[24:25] op_sel_hi:[0,1,1]
	v_cvt_pk_bf16_f32 v0, v10, v11
	v_cvt_pk_bf16_f32 v1, v12, v13
	v_cvt_pk_bf16_f32 v2, v14, v15
	v_cvt_pk_bf16_f32 v3, v16, v17
	global_store_dwordx4 v[6:7], v[0:3], off
	v_lshl_add_u64 v[6:7], v[6:7], 0, v[130:131]
	s_waitcnt vmcnt(16)
	v_lshlrev_b32_e32 v18, 16, v56
	v_and_b32_e32 v19, 0xffff0000, v56
	v_lshlrev_b32_e32 v20, 16, v57
	v_and_b32_e32 v21, 0xffff0000, v57
	v_lshlrev_b32_e32 v22, 16, v58
	v_and_b32_e32 v23, 0xffff0000, v58
	v_lshlrev_b32_e32 v24, 16, v59
	v_and_b32_e32 v25, 0xffff0000, v59
	v_pk_fma_f32 v[10:11], v[156:157], v[10:11], v[18:19] op_sel_hi:[0,1,1]
	v_pk_fma_f32 v[12:13], v[156:157], v[12:13], v[20:21] op_sel_hi:[0,1,1]
	v_pk_fma_f32 v[14:15], v[156:157], v[14:15], v[22:23] op_sel_hi:[0,1,1]
	v_pk_fma_f32 v[16:17], v[156:157], v[16:17], v[24:25] op_sel_hi:[0,1,1]
	v_cvt_pk_bf16_f32 v0, v10, v11
	v_cvt_pk_bf16_f32 v1, v12, v13
	v_cvt_pk_bf16_f32 v2, v14, v15
	v_cvt_pk_bf16_f32 v3, v16, v17
	global_store_dwordx4 v[6:7], v[0:3], off
	v_lshl_add_u64 v[6:7], v[6:7], 0, v[130:131]
	s_waitcnt vmcnt(16)
	v_lshlrev_b32_e32 v18, 16, v60
	v_and_b32_e32 v19, 0xffff0000, v60
	v_lshlrev_b32_e32 v20, 16, v61
	v_and_b32_e32 v21, 0xffff0000, v61
	v_lshlrev_b32_e32 v22, 16, v62
	v_and_b32_e32 v23, 0xffff0000, v62
	v_lshlrev_b32_e32 v24, 16, v63
	v_and_b32_e32 v25, 0xffff0000, v63
	v_pk_fma_f32 v[10:11], v[158:159], v[10:11], v[18:19] op_sel_hi:[0,1,1]
	v_pk_fma_f32 v[12:13], v[158:159], v[12:13], v[20:21] op_sel_hi:[0,1,1]
	v_pk_fma_f32 v[14:15], v[158:159], v[14:15], v[22:23] op_sel_hi:[0,1,1]
	v_pk_fma_f32 v[16:17], v[158:159], v[16:17], v[24:25] op_sel_hi:[0,1,1]
	v_cvt_pk_bf16_f32 v0, v10, v11
	v_cvt_pk_bf16_f32 v1, v12, v13
	v_cvt_pk_bf16_f32 v2, v14, v15
	v_cvt_pk_bf16_f32 v3, v16, v17
	global_store_dwordx4 v[6:7], v[0:3], off
	v_lshl_add_u64 v[6:7], v[6:7], 0, v[130:131]
	s_waitcnt vmcnt(16)
	v_lshlrev_b32_e32 v18, 16, v64
	v_and_b32_e32 v19, 0xffff0000, v64
	v_lshlrev_b32_e32 v20, 16, v65
	v_and_b32_e32 v21, 0xffff0000, v65
	v_lshlrev_b32_e32 v22, 16, v66
	v_and_b32_e32 v23, 0xffff0000, v66
	v_lshlrev_b32_e32 v24, 16, v67
	v_and_b32_e32 v25, 0xffff0000, v67
	v_pk_fma_f32 v[10:11], v[160:161], v[10:11], v[18:19] op_sel_hi:[0,1,1]
	v_pk_fma_f32 v[12:13], v[160:161], v[12:13], v[20:21] op_sel_hi:[0,1,1]
	v_pk_fma_f32 v[14:15], v[160:161], v[14:15], v[22:23] op_sel_hi:[0,1,1]
	v_pk_fma_f32 v[16:17], v[160:161], v[16:17], v[24:25] op_sel_hi:[0,1,1]
	v_cvt_pk_bf16_f32 v0, v10, v11
	v_cvt_pk_bf16_f32 v1, v12, v13
	v_cvt_pk_bf16_f32 v2, v14, v15
	v_cvt_pk_bf16_f32 v3, v16, v17
	global_store_dwordx4 v[6:7], v[0:3], off
	v_lshl_add_u64 v[6:7], v[6:7], 0, v[130:131]
	s_waitcnt vmcnt(16)
	v_lshlrev_b32_e32 v18, 16, v68
	v_and_b32_e32 v19, 0xffff0000, v68
	v_lshlrev_b32_e32 v20, 16, v69
	v_and_b32_e32 v21, 0xffff0000, v69
	v_lshlrev_b32_e32 v22, 16, v70
	v_and_b32_e32 v23, 0xffff0000, v70
	v_lshlrev_b32_e32 v24, 16, v71
	v_and_b32_e32 v25, 0xffff0000, v71
	v_pk_fma_f32 v[10:11], v[162:163], v[10:11], v[18:19] op_sel_hi:[0,1,1]
	v_pk_fma_f32 v[12:13], v[162:163], v[12:13], v[20:21] op_sel_hi:[0,1,1]
	v_pk_fma_f32 v[14:15], v[162:163], v[14:15], v[22:23] op_sel_hi:[0,1,1]
	v_pk_fma_f32 v[16:17], v[162:163], v[16:17], v[24:25] op_sel_hi:[0,1,1]
	v_cvt_pk_bf16_f32 v0, v10, v11
	v_cvt_pk_bf16_f32 v1, v12, v13
	v_cvt_pk_bf16_f32 v2, v14, v15
	v_cvt_pk_bf16_f32 v3, v16, v17
	global_store_dwordx4 v[6:7], v[0:3], off
	v_lshl_add_u64 v[6:7], v[6:7], 0, v[130:131]
	s_waitcnt vmcnt(16)
	v_lshlrev_b32_e32 v18, 16, v72
	v_and_b32_e32 v19, 0xffff0000, v72
	v_lshlrev_b32_e32 v20, 16, v73
	v_and_b32_e32 v21, 0xffff0000, v73
	v_lshlrev_b32_e32 v22, 16, v74
	v_and_b32_e32 v23, 0xffff0000, v74
	v_lshlrev_b32_e32 v24, 16, v75
	v_and_b32_e32 v25, 0xffff0000, v75
	v_pk_fma_f32 v[10:11], v[164:165], v[10:11], v[18:19] op_sel_hi:[0,1,1]
	v_pk_fma_f32 v[12:13], v[164:165], v[12:13], v[20:21] op_sel_hi:[0,1,1]
	v_pk_fma_f32 v[14:15], v[164:165], v[14:15], v[22:23] op_sel_hi:[0,1,1]
	v_pk_fma_f32 v[16:17], v[164:165], v[16:17], v[24:25] op_sel_hi:[0,1,1]
	v_cvt_pk_bf16_f32 v0, v10, v11
	v_cvt_pk_bf16_f32 v1, v12, v13
	v_cvt_pk_bf16_f32 v2, v14, v15
	v_cvt_pk_bf16_f32 v3, v16, v17
	global_store_dwordx4 v[6:7], v[0:3], off
	v_lshl_add_u64 v[6:7], v[6:7], 0, v[130:131]
	s_waitcnt vmcnt(16)
	v_lshlrev_b32_e32 v18, 16, v76
	v_and_b32_e32 v19, 0xffff0000, v76
	v_lshlrev_b32_e32 v20, 16, v77
	v_and_b32_e32 v21, 0xffff0000, v77
	v_lshlrev_b32_e32 v22, 16, v78
	v_and_b32_e32 v23, 0xffff0000, v78
	v_lshlrev_b32_e32 v24, 16, v79
	v_and_b32_e32 v25, 0xffff0000, v79
	v_pk_fma_f32 v[10:11], v[166:167], v[10:11], v[18:19] op_sel_hi:[0,1,1]
	v_pk_fma_f32 v[12:13], v[166:167], v[12:13], v[20:21] op_sel_hi:[0,1,1]
	v_pk_fma_f32 v[14:15], v[166:167], v[14:15], v[22:23] op_sel_hi:[0,1,1]
	v_pk_fma_f32 v[16:17], v[166:167], v[16:17], v[24:25] op_sel_hi:[0,1,1]
	v_cvt_pk_bf16_f32 v0, v10, v11
	v_cvt_pk_bf16_f32 v1, v12, v13
	v_cvt_pk_bf16_f32 v2, v14, v15
	v_cvt_pk_bf16_f32 v3, v16, v17
	global_store_dwordx4 v[6:7], v[0:3], off
	v_lshl_add_u64 v[6:7], v[6:7], 0, v[130:131]
	s_waitcnt vmcnt(16)
	v_lshlrev_b32_e32 v18, 16, v80
	v_and_b32_e32 v19, 0xffff0000, v80
	v_lshlrev_b32_e32 v20, 16, v81
	v_and_b32_e32 v21, 0xffff0000, v81
	v_lshlrev_b32_e32 v22, 16, v82
	v_and_b32_e32 v23, 0xffff0000, v82
	v_lshlrev_b32_e32 v24, 16, v83
	v_and_b32_e32 v25, 0xffff0000, v83
	v_pk_fma_f32 v[10:11], v[100:101], v[10:11], v[18:19] op_sel_hi:[0,1,1]
	v_pk_fma_f32 v[12:13], v[100:101], v[12:13], v[20:21] op_sel_hi:[0,1,1]
	v_pk_fma_f32 v[14:15], v[100:101], v[14:15], v[22:23] op_sel_hi:[0,1,1]
	v_pk_fma_f32 v[16:17], v[100:101], v[16:17], v[24:25] op_sel_hi:[0,1,1]
	v_cvt_pk_bf16_f32 v0, v10, v11
	v_cvt_pk_bf16_f32 v1, v12, v13
	v_cvt_pk_bf16_f32 v2, v14, v15
	v_cvt_pk_bf16_f32 v3, v16, v17
	global_store_dwordx4 v[6:7], v[0:3], off
	v_lshl_add_u64 v[6:7], v[6:7], 0, v[130:131]
	s_waitcnt vmcnt(16)
	v_lshlrev_b32_e32 v18, 16, v84
	v_and_b32_e32 v19, 0xffff0000, v84
	v_lshlrev_b32_e32 v20, 16, v85
	v_and_b32_e32 v21, 0xffff0000, v85
	v_lshlrev_b32_e32 v22, 16, v86
	v_and_b32_e32 v23, 0xffff0000, v86
	v_lshlrev_b32_e32 v24, 16, v87
	v_and_b32_e32 v25, 0xffff0000, v87
	v_pk_fma_f32 v[10:11], v[102:103], v[10:11], v[18:19] op_sel_hi:[0,1,1]
	v_pk_fma_f32 v[12:13], v[102:103], v[12:13], v[20:21] op_sel_hi:[0,1,1]
	v_pk_fma_f32 v[14:15], v[102:103], v[14:15], v[22:23] op_sel_hi:[0,1,1]
	v_pk_fma_f32 v[16:17], v[102:103], v[16:17], v[24:25] op_sel_hi:[0,1,1]
	v_cvt_pk_bf16_f32 v0, v10, v11
	v_cvt_pk_bf16_f32 v1, v12, v13
	v_cvt_pk_bf16_f32 v2, v14, v15
	v_cvt_pk_bf16_f32 v3, v16, v17
	global_store_dwordx4 v[6:7], v[0:3], off
	v_lshl_add_u64 v[6:7], v[6:7], 0, v[130:131]
	s_waitcnt vmcnt(16)
	v_lshlrev_b32_e32 v18, 16, v88
	v_and_b32_e32 v19, 0xffff0000, v88
	v_lshlrev_b32_e32 v20, 16, v89
	v_and_b32_e32 v21, 0xffff0000, v89
	v_lshlrev_b32_e32 v22, 16, v90
	v_and_b32_e32 v23, 0xffff0000, v90
	v_lshlrev_b32_e32 v24, 16, v91
	v_and_b32_e32 v25, 0xffff0000, v91
	v_pk_fma_f32 v[10:11], v[104:105], v[10:11], v[18:19] op_sel_hi:[0,1,1]
	v_pk_fma_f32 v[12:13], v[104:105], v[12:13], v[20:21] op_sel_hi:[0,1,1]
	v_pk_fma_f32 v[14:15], v[104:105], v[14:15], v[22:23] op_sel_hi:[0,1,1]
	v_pk_fma_f32 v[16:17], v[104:105], v[16:17], v[24:25] op_sel_hi:[0,1,1]
	v_cvt_pk_bf16_f32 v0, v10, v11
	v_cvt_pk_bf16_f32 v1, v12, v13
	v_cvt_pk_bf16_f32 v2, v14, v15
	v_cvt_pk_bf16_f32 v3, v16, v17
	global_store_dwordx4 v[6:7], v[0:3], off
	v_lshl_add_u64 v[6:7], v[6:7], 0, v[130:131]
	s_waitcnt vmcnt(16)
	v_lshlrev_b32_e32 v18, 16, v92
	v_and_b32_e32 v19, 0xffff0000, v92
	v_lshlrev_b32_e32 v20, 16, v93
	v_and_b32_e32 v21, 0xffff0000, v93
	v_lshlrev_b32_e32 v22, 16, v94
	v_and_b32_e32 v23, 0xffff0000, v94
	v_lshlrev_b32_e32 v24, 16, v95
	v_and_b32_e32 v25, 0xffff0000, v95
	v_pk_fma_f32 v[10:11], v[106:107], v[10:11], v[18:19] op_sel_hi:[0,1,1]
	v_pk_fma_f32 v[12:13], v[106:107], v[12:13], v[20:21] op_sel_hi:[0,1,1]
	v_pk_fma_f32 v[14:15], v[106:107], v[14:15], v[22:23] op_sel_hi:[0,1,1]
	v_pk_fma_f32 v[16:17], v[106:107], v[16:17], v[24:25] op_sel_hi:[0,1,1]
	v_cvt_pk_bf16_f32 v0, v10, v11
	v_cvt_pk_bf16_f32 v1, v12, v13
	v_cvt_pk_bf16_f32 v2, v14, v15
	v_cvt_pk_bf16_f32 v3, v16, v17
	global_store_dwordx4 v[6:7], v[0:3], off
	v_lshl_add_u64 v[6:7], v[6:7], 0, v[130:131]
	s_waitcnt vmcnt(16)
	v_lshlrev_b32_e32 v18, 16, v96
	v_and_b32_e32 v19, 0xffff0000, v96
	v_lshlrev_b32_e32 v20, 16, v97
	v_and_b32_e32 v21, 0xffff0000, v97
	v_lshlrev_b32_e32 v22, 16, v98
	v_and_b32_e32 v23, 0xffff0000, v98
	v_lshlrev_b32_e32 v24, 16, v99
	v_and_b32_e32 v25, 0xffff0000, v99
	v_pk_fma_f32 v[10:11], v[108:109], v[10:11], v[18:19] op_sel_hi:[0,1,1]
	v_pk_fma_f32 v[12:13], v[108:109], v[12:13], v[20:21] op_sel_hi:[0,1,1]
	v_pk_fma_f32 v[14:15], v[108:109], v[14:15], v[22:23] op_sel_hi:[0,1,1]
	v_pk_fma_f32 v[16:17], v[108:109], v[16:17], v[24:25] op_sel_hi:[0,1,1]
	s_add_i32 s13, s13, 1
	s_cmp_lt_u32 s13, 4
	s_cbranch_scc1 .Lscan16_loop
	s_branch .LBB0_1473
.LBB0_1480:
	s_or_b64 exec, exec, s[2:3]
	s_mov_b32 s84, 0
.Lkvp1_entry:
	v_readlane_b32 s4, v244, 0
	v_readlane_b32 s5, v244, 1
	v_readlane_b32 s6, v244, 2
	v_readlane_b32 s7, v244, 3
	v_readlane_b32 s8, v244, 4
	v_readlane_b32 s9, v244, 5
	v_readlane_b32 s10, v244, 6
	v_readlane_b32 s11, v244, 7
	s_mov_b64 s[4:5], s[8:9]
	s_mov_b64 s[6:7], s[10:11]
	s_add_u32 s33, s6, 0x18800000
	s_addc_u32 s38, s7, 0
	s_abs_i32 s39, s86
	v_cvt_f32_u32_e32 v0, s39
	s_sub_i32 s2, 0, s39
	s_add_i32 s40, s86, s89
	v_lshlrev_b32_e32 v1, 4, v182
	v_rcp_iflag_f32_e32 v0, v0
	v_and_b32_e32 v2, 32, v182
	v_bitop3_b32 v142, v1, v2, 48 bitop3:0x6c
	v_lshrrev_b32_e32 v2, 5, v182
	v_mul_f32_e32 v0, 0x4f7ffffe, v0
	v_cvt_u32_f32_e32 v0, v0
	v_lshrrev_b32_e32 v4, 1, v182
	v_and_b32_e32 v2, 4, v2
	v_bfe_u32 v3, v182, 2, 2
	v_readfirstlane_b32 s41, v0
	s_mul_i32 s2, s2, s41
	s_mul_hi_u32 s2, s41, s2
	s_add_i32 s41, s41, s2
	s_mul_hi_u32 s2, s41, 0xc0
	s_mul_i32 s2, s2, s39
	s_sub_i32 s2, 0xc0, s2
	s_sub_i32 s3, s2, s39
	s_cmp_ge_u32 s2, s39
	s_cselect_b32 s2, s3, s2
	s_sub_i32 s3, s2, s39
	s_cmp_ge_u32 s2, s39
	s_cselect_b32 s2, s3, s2
	s_sub_i32 s2, s40, s2
	s_ashr_i32 s3, s2, 31
	s_abs_i32 s2, s2
	s_mul_hi_u32 s4, s2, s41
	s_mul_i32 s4, s4, s39
	s_sub_i32 s2, s2, s4
	s_sub_i32 s4, s2, s39
	s_cmp_ge_u32 s2, s39
	s_cselect_b32 s2, s4, s2
	s_sub_i32 s4, s2, s39
	s_cmp_ge_u32 s2, s39
	s_cselect_b32 s2, s4, s2
	s_xor_b32 s2, s2, s3
	v_and_b32_e32 v148, 24, v4
	v_bfe_u32 v143, v182, 2, 4
	s_sub_i32 s42, s2, s3
	v_or3_b32 v2, v2, v3, v148
	v_lshrrev_b32_e32 v3, 3, v182
	s_movk_i32 s2, 0x70
	v_and_b32_e32 v146, 64, v182
	v_and_or_b32 v4, v3, s2, v143
	s_movk_i32 s2, 0x60
	v_add_u32_e32 v147, 0x2000, v1
	v_or_b32_e32 v0, v142, v146
	v_and_or_b32 v3, v3, s2, v2
	v_lshrrev_b32_e32 v1, 7, v147
	s_movk_i32 s2, 0xf0
	v_lshl_or_b32 v130, v3, 11, v0
	v_and_or_b32 v3, v1, s2, v143
	s_movk_i32 s2, 0xe0
	v_and_or_b32 v1, v1, s2, v2
	v_lshl_or_b32 v128, v4, 11, v0
	v_lshl_or_b32 v132, v3, 11, v0
	v_lshl_or_b32 v134, v1, 11, v0
	v_lshlrev_b32_e32 v0, 6, v182
	v_lshlrev_b32_e32 v1, 2, v182
	v_lshlrev_b32_e32 v150, 1, v148
	v_and_b32_e32 v0, 0x3c0, v0
	v_and_b32_e32 v1, 32, v1
	v_readfirstlane_b32 s11, v182
	v_and_b32_e32 v149, 15, v182
	s_cmp_lg_u32 s84, 0
	s_cselect_b32 s42, 0x3e8, s42
	s_cmp_gt_i32 s42, 39
	v_bitop3_b32 v151, v150, v1, v0 bitop3:0x36
	s_cbranch_scc1 .LBB0_1496
	v_readlane_b32 s12, v244, 0
	v_readlane_b32 s16, v244, 4
	v_readlane_b32 s17, v244, 5
	v_readlane_b32 s18, v244, 6
	v_readlane_b32 s19, v244, 7
	s_mov_b64 s[4:5], s[16:17]
	s_mov_b64 s[6:7], s[18:19]
	s_add_u32 s43, s6, 0x1f400000
	s_addc_u32 s44, s7, 0
	s_ashr_i32 s46, s42, 31
	s_lshr_b32 s2, s46, 29
	s_add_i32 s2, s42, s2
	s_lshr_b32 s8, s11, 6
	s_ashr_i32 s3, s2, 3
	s_and_b32 s2, s2, -8
	s_lshr_b32 s12, s11, 8
	s_lshl_b32 s45, s8, 10
	s_sub_i32 s2, s42, s2
	s_cmp_lt_i32 s2, 0
	s_cselect_b32 s4, 6, 5
	s_mul_i32 s2, s2, s4
	s_add_i32 s2, s2, s3
	s_ashr_i32 s3, s2, 31
	s_lshr_b32 s3, s3, 27
	s_add_i32 s3, s2, s3
	s_ashr_i32 s4, s3, 5
	s_lshl_b32 s4, s4, 3
	s_sub_i32 s5, 10, s4
	s_min_u32 s5, s5, 8
	s_andn2_b32 s3, s3, 31
	s_sub_i32 s6, s2, s3
	v_cvt_f32_ubyte0_e32 v1, s5
	v_cvt_f32_i32_e32 v0, s6
	v_rcp_iflag_f32_e32 v2, v1
	s_ashr_i32 s2, s6, 30
	s_or_b32 s7, s2, 1
	v_mov_b32_e32 v137, 0
	v_mul_f32_e32 v2, v0, v2
	v_trunc_f32_e32 v2, v2
	v_fma_f32 v0, -v2, v1, v0
	v_cvt_i32_f32_e32 v2, v2
	v_cmp_ge_f32_e64 s[2:3], |v0|, v1
	s_and_b64 s[2:3], s[2:3], exec
	s_cselect_b32 s2, s7, 0
	v_readfirstlane_b32 s3, v2
	s_add_i32 s10, s3, s2
	s_mul_i32 s2, s10, s5
	s_sub_i32 s2, s6, s2
	s_sext_i32_i8 s2, s2
	s_add_i32 s28, s4, s2
	s_ashr_i32 s29, s28, 31
	s_bfe_i64 s[4:5], s[10:11], 0x80000
	s_lshl_b64 s[2:3], s[28:29], 19
	s_lshl_b64 s[4:5], s[4:5], 19
	s_add_u32 s34, s43, s4
	s_addc_u32 s35, s44, s5
	s_add_i32 s47, s45, 0
	s_add_i32 m0, s47, 0x10000
	v_mov_b32_e32 v131, v137
	global_load_lds_dwordx4 v130, s[34:35]
	s_add_i32 m0, s47, 0x12000
	s_add_u32 s4, s34, 0x40000
	global_load_lds_dwordx4 v134, s[34:35]
	s_addc_u32 s5, s35, 0
	s_add_i32 m0, s47, 0x14000
	v_mov_b32_e32 v135, v137
	global_load_lds_dwordx4 v130, s[4:5]
	s_add_i32 m0, s47, 0x16000
	s_add_u32 s30, s33, s2
	s_addc_u32 s31, s38, s3
	s_add_i32 s48, s47, 0x2000
	global_load_lds_dwordx4 v134, s[4:5]
	s_mov_b32 m0, s47
	s_add_u32 s2, s30, 0x40000
	global_load_lds_dwordx4 v128, s[30:31]
	s_mov_b32 m0, s48
	s_addc_u32 s3, s31, 0
	s_add_i32 s49, s47, 0x4000
	global_load_lds_dwordx4 v132, s[30:31]
	s_mov_b32 m0, s49
	s_add_i32 s50, s47, 0x6000
	global_load_lds_dwordx4 v128, s[2:3]
	s_mov_b32 m0, s50
	v_mov_b32_e32 v129, v137
	global_load_lds_dwordx4 v132, s[2:3]
	v_mov_b32_e32 v133, v137
	s_cmp_eq_u32 s12, 1
	v_lshl_add_u64 v[6:7], s[34:35], 0, v[130:131]
	v_lshl_add_u64 v[2:3], s[34:35], 0, v[134:135]
	s_mov_b64 s[2:3], 0x40000
	v_lshl_add_u64 v[0:1], s[30:31], 0, v[128:129]
	s_cselect_b64 s[4:5], -1, 0
	s_cmp_lg_u32 s12, 1
	v_lshl_add_u64 v[4:5], s[30:31], 0, v[132:133]
	v_readlane_b32 s13, v244, 1
	v_readlane_b32 s14, v244, 2
	v_readlane_b32 s15, v244, 3
	s_cbranch_scc1 .LBB0_1483
	s_barrier

.LBB0_1496:
	s_mul_hi_u32 s2, s41, 0xe8
	s_mul_i32 s2, s2, s39
	s_sub_i32 s2, 0xe8, s2
	s_sub_i32 s3, s2, s39
	s_cmp_ge_u32 s2, s39
	s_cselect_b32 s2, s3, s2
	s_sub_i32 s3, s2, s39
	s_cmp_ge_u32 s2, s39
	s_cselect_b32 s2, s3, s2
	s_sub_i32 s2, s40, s2
	s_ashr_i32 s3, s2, 31
	s_abs_i32 s2, s2
	s_mul_hi_u32 s4, s2, s41
	s_mul_i32 s4, s4, s39
	s_sub_i32 s2, s2, s4
	s_sub_i32 s4, s2, s39
	s_cmp_ge_u32 s2, s39
	s_cselect_b32 s2, s4, s2
	s_sub_i32 s4, s2, s39
	s_cmp_ge_u32 s2, s39
	s_cselect_b32 s2, s4, s2
	s_xor_b32 s2, s2, s3
	s_sub_i32 s28, s2, s3
	s_cmp_lg_u32 s84, 0
	s_cbranch_scc1 .Lkv2_p1
	s_cmp_gt_i32 s28, 23
	s_branch .Lkv2_j
.Lkv2_p1:
	s_mov_b32 s28, s85
	s_cmp_gt_i32 s28, 39
.Lkv2_j:
	v_readfirstlane_b32 s9, v182
	s_cbranch_scc1 .LBB0_1512
	v_readlane_b32 s12, v244, 0
	v_readlane_b32 s16, v244, 4
	v_readlane_b32 s17, v244, 5
	v_readlane_b32 s18, v244, 6
	v_readlane_b32 s19, v244, 7
	s_mov_b64 s[4:5], s[16:17]
	s_mov_b64 s[6:7], s[18:19]
	s_add_u32 s29, s6, 0x1f600000
	s_addc_u32 s30, s7, 0
	s_ashr_i32 s34, s28, 31
	s_lshr_b32 s2, s34, 29
	s_add_i32 s2, s28, s2
	s_lshr_b32 s6, s9, 6
	s_ashr_i32 s3, s2, 3
	s_and_b32 s2, s2, -8
	s_lshr_b32 s10, s9, 8
	s_lshl_b32 s31, s6, 10
	s_sub_i32 s2, s28, s2
	s_cmp_lt_i32 s2, 0
	s_cselect_b32 s4, 6, 5
	s_mul_i32 s2, s2, s4
	s_add_i32 s2, s2, s3
	s_mul_hi_i32 s3, s2, 0x66666667
	s_lshr_b32 s4, s3, 31
	s_ashr_i32 s3, s3, 5
	s_add_i32 s3, s3, s4
	s_lshl_b32 s4, s3, 3
	s_sub_i32 s5, 4, s4
	s_min_u32 s5, s5, 8
	s_mulk_i32 s3, 0x50
	s_sub_i32 s7, s2, s3
	v_cvt_f32_ubyte0_e32 v1, s5
	v_cvt_f32_i32_e32 v0, s7
	v_rcp_iflag_f32_e32 v2, v1
	s_ashr_i32 s2, s7, 30
	s_or_b32 s8, s2, 1
	v_mov_b32_e32 v137, 0
	v_mul_f32_e32 v2, v0, v2
	v_trunc_f32_e32 v2, v2
	v_fma_f32 v0, -v2, v1, v0
	v_cvt_i32_f32_e32 v2, v2
	v_cmp_ge_f32_e64 s[2:3], |v0|, v1
	s_and_b64 s[2:3], s[2:3], exec
	s_cselect_b32 s2, s8, 0
	v_readfirstlane_b32 s3, v2
	s_add_i32 s8, s3, s2
	s_mul_i32 s2, s8, s5
	s_sub_i32 s2, s7, s2
	s_sext_i32_i8 s2, s2
	s_add_i32 s20, s4, s2
	s_ashr_i32 s21, s20, 31
	s_bfe_i64 s[4:5], s[8:9], 0x80000
	s_lshl_b64 s[2:3], s[20:21], 19
	s_lshl_b64 s[4:5], s[4:5], 19
	s_add_u32 s24, s33, s4
	s_addc_u32 s25, s38, s5
	s_add_i32 s35, s31, 0
	s_add_i32 m0, s35, 0x10000
	v_mov_b32_e32 v131, v137
	global_load_lds_dwordx4 v130, s[24:25]
	s_add_i32 m0, s35, 0x12000
	s_add_u32 s4, s24, 0x40000
	global_load_lds_dwordx4 v134, s[24:25]
	s_addc_u32 s5, s25, 0
	s_add_i32 m0, s35, 0x14000
	v_mov_b32_e32 v135, v137
	global_load_lds_dwordx4 v130, s[4:5]
	s_add_i32 m0, s35, 0x16000
	s_add_u32 s22, s29, s2
	s_addc_u32 s23, s30, s3
	s_add_i32 s36, s35, 0x2000
	global_load_lds_dwordx4 v134, s[4:5]
	s_mov_b32 m0, s35
	s_add_u32 s2, s22, 0x40000
	global_load_lds_dwordx4 v128, s[22:23]
	s_mov_b32 m0, s36
	s_addc_u32 s3, s23, 0
	s_add_i32 s37, s35, 0x4000
	global_load_lds_dwordx4 v132, s[22:23]
	s_mov_b32 m0, s37
	s_add_i32 s39, s35, 0x6000
	global_load_lds_dwordx4 v128, s[2:3]
	s_mov_b32 m0, s39
	v_mov_b32_e32 v129, v137
	global_load_lds_dwordx4 v132, s[2:3]
	v_mov_b32_e32 v133, v137
	s_cmp_eq_u32 s10, 1
	s_mov_b32 s40, 0
	v_lshl_add_u64 v[6:7], s[24:25], 0, v[130:131]
	v_lshl_add_u64 v[4:5], s[24:25], 0, v[134:135]
	v_lshl_add_u64 v[0:1], s[22:23], 0, v[128:129]
	s_cselect_b64 s[2:3], -1, 0
	s_cmp_lg_u32 s10, 1
	v_lshl_add_u64 v[2:3], s[22:23], 0, v[132:133]
	v_readlane_b32 s13, v244, 1
	v_readlane_b32 s14, v244, 2
	v_readlane_b32 s15, v244, 3
	s_cbranch_scc1 .LBB0_1499
	s_barrier

.LBB0_1511:
	s_waitcnt vmcnt(0)
	s_barrier
	s_cmp_lg_u32 s84, 0
	s_cbranch_scc1 .Lkvp1_ret

.LBB0_1947:
	v_readlane_b32 s4, v244, 47
	s_cmp_lt_i32 s4, 10
	s_cselect_b64 s[2:3], -1, 0
	s_and_b64 s[2:3], s[2:3], s[0:1]
	s_cmpk_lt_i32 s69, 0x600
	s_cselect_b64 s[0:1], -1, 0
	s_and_b64 s[0:1], s[2:3], s[0:1]
	s_andn2_b64 vcc, exec, s[0:1]
	v_readlane_b32 s5, v244, 48
	v_readlane_b32 s6, v244, 49
	v_readlane_b32 s7, v244, 50
	s_cbranch_vccnz .LBB0_1956
	v_and_b32_e32 v249, 63, v182
	v_readlane_b32 s4, v244, 6
	v_readlane_b32 s5, v244, 7
	v_readlane_b32 s6, v244, 39
	v_readlane_b32 s7, v244, 40
	v_readlane_b32 s8, v244, 41
	v_readlane_b32 s9, v244, 42
	v_lshlrev_b32_e32 v242, 2, v249
	s_nop 3
	global_load_dword v216, v242, s[6:7] offset:0
	global_load_dword v217, v242, s[6:7] offset:256
	global_load_dword v218, v242, s[6:7] offset:512
	global_load_dword v219, v242, s[6:7] offset:768
	global_load_dword v220, v242, s[8:9] offset:0
	global_load_dword v221, v242, s[8:9] offset:256
	global_load_dword v222, v242, s[8:9] offset:512
	global_load_dword v223, v242, s[8:9] offset:768
	v_and_b32_e32 v243, 15, v182
	v_bfe_u32 v245, v182, 4, 2
	v_lshl_or_b32 v246, s88, 4, v243
	v_lshlrev_b32_e32 v228, 11, v246
	v_lshl_add_u32 v238, v245, 3, v228
	v_lshl_add_u32 v228, v245, 4, v228
	v_add_u32_e32 v229, 0x40000, v228
	v_add_u32_e32 v239, 0x40000, v238
	v_lshlrev_b32_e32 v230, 4, v246
	v_mul_u32_u24_e32 v231, 528, v243
	v_lshl_add_u32 v232, v245, 3, v231
	v_lshl_add_u32 v231, v245, 4, v231
	v_lshrrev_b32_e32 v243, 5, v182
	v_and_b32_e32 v245, 31, v182
	v_lshlrev_b32_e32 v245, 4, v245
	v_lshl_add_u32 v224, v243, 11, v245
	v_mul_u32_u24_e32 v225, 5120, v243
	v_add_u32_e32 v225, v225, v245
	v_mul_u32_u24_e32 v226, 528, v243
	v_add_u32_e32 v226, v226, v245
	v_add_u32_e32 v227, 67584, v226
	v_and_b32_e32 v250, 3, v243
	v_bfe_u32 v242, v243, 2, 1
	v_lshl_or_b32 v250, v242, 4, v250
	v_bfe_u32 v242, v243, 3, 1
	v_lshl_or_b32 v250, v242, 2, v250
	v_mul_u32_u24_e32 v250, 528, v250
	v_add_u32_e32 v250, v250, v245
	v_add_u32_e32 v251, 67584, v250
	v_xor_b32_e32 v236, 16, v249
	v_lshlrev_b32_e32 v236, 2, v236
	v_xor_b32_e32 v237, 32, v249
	v_lshlrev_b32_e32 v237, 2, v237
	v_mov_b32_e32 v181, 0x358637bd
	s_waitcnt vmcnt(0)
	v_mul_f32_e32 v216, v216, v220
	v_mul_f32_e32 v217, v217, v221
	v_mul_f32_e32 v218, v218, v222
	v_mul_f32_e32 v219, v219, v223
	v_max_f32_e64 v216, |v216|, |v217|
	v_max_f32_e64 v218, |v218|, |v219|
	v_max_f32_e32 v216, v216, v218
	v_xor_b32_e32 v242, 1, v249
	v_lshlrev_b32_e32 v242, 2, v242
	ds_bpermute_b32 v243, v242, v216
	s_waitcnt lgkmcnt(0)
	v_max_f32_e32 v216, v216, v243
	v_xor_b32_e32 v242, 2, v249
	v_lshlrev_b32_e32 v242, 2, v242
	ds_bpermute_b32 v243, v242, v216
	s_waitcnt lgkmcnt(0)
	v_max_f32_e32 v216, v216, v243
	v_xor_b32_e32 v242, 4, v249
	v_lshlrev_b32_e32 v242, 2, v242
	ds_bpermute_b32 v243, v242, v216
	s_waitcnt lgkmcnt(0)
	v_max_f32_e32 v216, v216, v243
	v_xor_b32_e32 v242, 8, v249
	v_lshlrev_b32_e32 v242, 2, v242
	ds_bpermute_b32 v243, v242, v216
	s_waitcnt lgkmcnt(0)
	v_max_f32_e32 v216, v216, v243
	v_xor_b32_e32 v242, 16, v249
	v_lshlrev_b32_e32 v242, 2, v242
	ds_bpermute_b32 v243, v242, v216
	s_waitcnt lgkmcnt(0)
	v_max_f32_e32 v216, v216, v243
	v_xor_b32_e32 v242, 32, v249
	v_lshlrev_b32_e32 v242, 2, v242
	ds_bpermute_b32 v243, v242, v216
	s_waitcnt lgkmcnt(0)
	v_max_f32_e32 v216, v216, v243
	v_mul_f32_e32 v180, 0x41b8aa3b, v216
	s_and_b32 s0, s69, 31
	s_lshr_b32 s1, s69, 8
	s_lshl_b32 s1, s1, 5
	s_add_i32 s1, s1, s0
	s_mul_i32 s0, s1, 2731
	s_lshr_b32 s0, s0, 16
	s_mul_i32 s17, s0, 24
	s_sub_i32 s1, s1, s17
	s_bfe_u32 s17, s69, 0x30005
	s_mul_i32 s17, s17, 24
	s_add_i32 s1, s1, s17
	s_lshl_b32 s11, s1, 19
	s_lshl_b32 s12, s0, 9
	s_add_u32 s11, s11, s12
	s_add_u32 s12, s11, 0xf000000
	s_add_u32 s10, s4, s12
	s_addc_u32 s11, s5, 0
	s_lshl_b32 s12, s1, 12
	s_lshl_b32 s13, s0, 2
	s_add_u32 s12, s12, s13
	s_add_u32 s12, s12, 0x1fa60000
	s_add_u32 s12, s4, s12
	s_addc_u32 s13, s5, 0
	global_load_dwordx4 v[0:3], v228, s[10:11] offset:0
	global_load_dwordx4 v[4:7], v228, s[10:11] offset:64
	global_load_dwordx4 v[8:11], v228, s[10:11] offset:128
	global_load_dwordx4 v[12:15], v228, s[10:11] offset:192
	global_load_dwordx4 v[16:19], v228, s[10:11] offset:256
	global_load_dwordx4 v[20:23], v228, s[10:11] offset:320
	global_load_dwordx4 v[24:27], v228, s[10:11] offset:384
	global_load_dwordx4 v[28:31], v228, s[10:11] offset:448
	global_load_dwordx4 v[32:35], v229, s[10:11] offset:0
	global_load_dwordx4 v[36:39], v229, s[10:11] offset:64
	global_load_dwordx4 v[40:43], v229, s[10:11] offset:128
	global_load_dwordx4 v[44:47], v229, s[10:11] offset:192
	global_load_dwordx4 v[48:51], v229, s[10:11] offset:256
	global_load_dwordx4 v[52:55], v229, s[10:11] offset:320
	global_load_dwordx4 v[56:59], v229, s[10:11] offset:384
	global_load_dwordx4 v[60:63], v229, s[10:11] offset:448
	global_load_dword v247, v230, s[12:13]
	global_load_dword v248, v230, s[12:13] offset:2048
	s_lshr_b32 s10, s1, 5
	s_sub_i32 s11, s1, 64
	s_lshr_b32 s11, s11, 4
	s_add_i32 s11, s11, 2
	s_cmp_lt_u32 s1, 64
	s_cselect_b32 s10, s10, s11
	s_lshl_b32 s11, s10, 19
	s_lshl_b32 s12, s0, 9
	s_add_u32 s11, s11, s12
	s_add_u32 s11, s11, 0x19040000
	s_add_u32 s6, s4, s11
	s_addc_u32 s7, s5, 0
	global_load_dwordx4 v[184:187], v224, s[6:7]
	s_add_u32 s6, s6, 0x8000
	s_addc_u32 s7, s7, 0
	global_load_dwordx4 v[188:191], v224, s[6:7]
	s_add_u32 s6, s6, 0x8000
	s_addc_u32 s7, s7, 0
	global_load_dwordx4 v[192:195], v224, s[6:7]
	s_add_u32 s6, s6, 0x8000
	s_addc_u32 s7, s7, 0
	global_load_dwordx4 v[196:199], v224, s[6:7]
	s_add_u32 s6, s6, 0x8000
	s_addc_u32 s7, s7, 0
	global_load_dwordx4 v[200:203], v224, s[6:7]
	s_add_u32 s6, s6, 0x8000
	s_addc_u32 s7, s7, 0
	global_load_dwordx4 v[204:207], v224, s[6:7]
	s_add_u32 s6, s6, 0x8000
	s_addc_u32 s7, s7, 0
	global_load_dwordx4 v[208:211], v224, s[6:7]
	s_add_u32 s6, s6, 0x8000
	s_addc_u32 s7, s7, 0
	global_load_dwordx4 v[212:215], v224, s[6:7]
.Lxa_unit:
	s_and_b32 s0, s69, 31
	s_lshr_b32 s1, s69, 8
	s_lshl_b32 s1, s1, 5
	s_add_i32 s1, s1, s0
	s_mul_i32 s0, s1, 2731
	s_lshr_b32 s0, s0, 16
	s_mul_i32 s17, s0, 24
	s_sub_i32 s1, s1, s17
	s_bfe_u32 s17, s69, 0x30005
	s_mul_i32 s17, s17, 24
	s_add_i32 s1, s1, s17
	s_lshr_b32 s10, s1, 5
	s_sub_i32 s11, s1, 64
	s_lshr_b32 s11, s11, 4
	s_add_i32 s11, s11, 2
	s_cmp_lt_u32 s1, 64
	s_cselect_b32 s10, s10, s11
	s_lshl_b32 s11, s10, 19
	s_lshl_b32 s12, s0, 9
	s_add_u32 s11, s11, s12
	s_add_u32 s11, s11, 0x19000000
	s_add_u32 s6, s4, s11
	s_addc_u32 s7, s5, 0
	s_mul_i32 s11, s0, 0x140000
	s_lshl_b32 s12, s10, 9
	s_add_u32 s11, s11, s12
	s_add_u32 s11, s11, 0x19800000
	s_add_u32 s8, s4, s11
	s_addc_u32 s9, s5, 0
	s_lshl_b32 s12, s1, 19
	s_lshl_b32 s13, s0, 9
	s_add_u32 s12, s12, s13
	s_add_u32 s12, s12, 0x9000000
	s_add_u32 s14, s4, s12
	s_addc_u32 s15, s5, 0
	global_load_dwordx4 v[128:131], v224, s[6:7]
	s_add_u32 s6, s6, 0x8000
	s_addc_u32 s7, s7, 0
	global_load_dwordx4 v[132:135], v224, s[6:7]
	s_add_u32 s6, s6, 0x8000
	s_addc_u32 s7, s7, 0
	global_load_dwordx4 v[136:139], v224, s[6:7]
	s_add_u32 s6, s6, 0x8000
	s_addc_u32 s7, s7, 0
	global_load_dwordx4 v[140:143], v224, s[6:7]
	s_add_u32 s6, s6, 0x8000
	s_addc_u32 s7, s7, 0
	global_load_dwordx4 v[144:147], v224, s[6:7]
	s_add_u32 s6, s6, 0x8000
	s_addc_u32 s7, s7, 0
	global_load_dwordx4 v[148:151], v224, s[6:7]
	s_add_u32 s6, s6, 0x8000
	s_addc_u32 s7, s7, 0
	global_load_dwordx4 v[152:155], v224, s[6:7]
	s_add_u32 s6, s6, 0x8000
	s_addc_u32 s7, s7, 0
	global_load_dwordx4 v[156:159], v224, s[6:7]
	s_add_u32 s6, s6, 0x8000
	s_addc_u32 s7, s7, 0
	s_waitcnt vmcnt(4)
	ds_write_b128 v226, v[128:131] offset:0
	ds_write_b128 v226, v[132:135] offset:8448
	ds_write_b128 v226, v[136:139] offset:16896
	ds_write_b128 v226, v[140:143] offset:25344
	s_waitcnt vmcnt(0)
	ds_write_b128 v226, v[144:147] offset:33792
	ds_write_b128 v226, v[148:151] offset:42240
	ds_write_b128 v226, v[152:155] offset:50688
	ds_write_b128 v226, v[156:159] offset:59136
	ds_write_b128 v227, v[184:187] offset:0
	ds_write_b128 v227, v[188:191] offset:8448
	ds_write_b128 v227, v[192:195] offset:16896
	ds_write_b128 v227, v[196:199] offset:25344
	ds_write_b128 v227, v[200:203] offset:33792
	ds_write_b128 v227, v[204:207] offset:42240
	ds_write_b128 v227, v[208:211] offset:50688
	ds_write_b128 v227, v[212:215] offset:59136
	s_waitcnt vmcnt(0)
	v_fmamk_f32 v178, v247, 0x3b800000, v181
	v_fmamk_f32 v179, v248, 0x3b800000, v181
	v_rsq_f32_e32 v178, v178
	v_rsq_f32_e32 v179, v179
	v_mov_b32_e32 v176, 0
	v_mov_b32_e32 v177, 0
	v_mul_f32_e32 v178, 0x3db8aa3b, v178
	v_mul_f32_e32 v179, 0x3db8aa3b, v179
	s_waitcnt lgkmcnt(0)
	s_barrier
	v_mov_b32_e32 v233, v231
	ds_read_b128 v[128:131], v233 offset:0
	ds_read_b128 v[132:135], v233 offset:64
	ds_read_b128 v[136:139], v233 offset:128
	ds_read_b128 v[140:143], v233 offset:192
	ds_read_b128 v[144:147], v233 offset:256
	ds_read_b128 v[148:151], v233 offset:320
	ds_read_b128 v[152:155], v233 offset:384
	ds_read_b128 v[156:159], v233 offset:448
	s_waitcnt lgkmcnt(0)
	ds_read_b128 v[184:187], v233 offset:8448
	ds_read_b128 v[188:191], v233 offset:8512
	ds_read_b128 v[192:195], v233 offset:8576
	ds_read_b128 v[196:199], v233 offset:8640
	ds_read_b128 v[200:203], v233 offset:8704
	ds_read_b128 v[204:207], v233 offset:8768
	ds_read_b128 v[208:211], v233 offset:8832
	ds_read_b128 v[212:215], v233 offset:8896
	v_mfma_f32_16x16x32_bf16 v[160:163], v[128:131], v[0:3], 0
	v_mfma_f32_16x16x32_bf16 v[164:167], v[128:131], v[32:35], 0
	v_mfma_f32_16x16x32_bf16 v[160:163], v[132:135], v[4:7], v[160:163]
	v_mfma_f32_16x16x32_bf16 v[164:167], v[132:135], v[36:39], v[164:167]
	v_mfma_f32_16x16x32_bf16 v[160:163], v[136:139], v[8:11], v[160:163]
	v_mfma_f32_16x16x32_bf16 v[164:167], v[136:139], v[40:43], v[164:167]
	v_mfma_f32_16x16x32_bf16 v[160:163], v[140:143], v[12:15], v[160:163]
	v_mfma_f32_16x16x32_bf16 v[164:167], v[140:143], v[44:47], v[164:167]
	v_mfma_f32_16x16x32_bf16 v[160:163], v[144:147], v[16:19], v[160:163]
	v_mfma_f32_16x16x32_bf16 v[164:167], v[144:147], v[48:51], v[164:167]
	v_mfma_f32_16x16x32_bf16 v[160:163], v[148:151], v[20:23], v[160:163]
	v_mfma_f32_16x16x32_bf16 v[164:167], v[148:151], v[52:55], v[164:167]
	v_mfma_f32_16x16x32_bf16 v[160:163], v[152:155], v[24:27], v[160:163]
	v_mfma_f32_16x16x32_bf16 v[164:167], v[152:155], v[56:59], v[164:167]
	v_mfma_f32_16x16x32_bf16 v[160:163], v[156:159], v[28:31], v[160:163]
	v_mfma_f32_16x16x32_bf16 v[164:167], v[156:159], v[60:63], v[164:167]
	s_waitcnt lgkmcnt(0)
	ds_read_b128 v[128:131], v233 offset:16896
	ds_read_b128 v[132:135], v233 offset:16960
	ds_read_b128 v[136:139], v233 offset:17024
	ds_read_b128 v[140:143], v233 offset:17088
	ds_read_b128 v[144:147], v233 offset:17152
	ds_read_b128 v[148:151], v233 offset:17216
	ds_read_b128 v[152:155], v233 offset:17280
	ds_read_b128 v[156:159], v233 offset:17344
	v_mfma_f32_16x16x32_bf16 v[168:171], v[184:187], v[0:3], 0
	v_fma_f32 v216, v160, v178, -v180
	v_fma_f32 v217, v161, v178, -v180
	v_mfma_f32_16x16x32_bf16 v[172:175], v[184:187], v[32:35], 0
	v_fma_f32 v218, v162, v178, -v180
	v_fma_f32 v219, v163, v178, -v180
	v_mfma_f32_16x16x32_bf16 v[168:171], v[188:191], v[4:7], v[168:171]
	v_exp_f32_e32 v216, v216
	v_exp_f32_e32 v217, v217
	v_mfma_f32_16x16x32_bf16 v[172:175], v[188:191], v[36:39], v[172:175]
	v_exp_f32_e32 v218, v218
	v_exp_f32_e32 v219, v219
	v_mfma_f32_16x16x32_bf16 v[168:171], v[192:195], v[8:11], v[168:171]
	v_fma_f32 v220, v164, v179, -v180
	v_fma_f32 v221, v165, v179, -v180
	v_mfma_f32_16x16x32_bf16 v[172:175], v[192:195], v[40:43], v[172:175]
	v_fma_f32 v222, v166, v179, -v180
	v_fma_f32 v223, v167, v179, -v180
	v_mfma_f32_16x16x32_bf16 v[168:171], v[196:199], v[12:15], v[168:171]
	v_exp_f32_e32 v220, v220
	v_exp_f32_e32 v221, v221
	v_mfma_f32_16x16x32_bf16 v[172:175], v[196:199], v[44:47], v[172:175]
	v_exp_f32_e32 v222, v222
	v_exp_f32_e32 v223, v223
	v_mfma_f32_16x16x32_bf16 v[168:171], v[200:203], v[16:19], v[168:171]
	v_add_f32_e32 v176, v176, v216
	v_add_f32_e32 v176, v176, v217
	v_mfma_f32_16x16x32_bf16 v[172:175], v[200:203], v[48:51], v[172:175]
	v_cvt_pk_bf16_f32 v64, v216, v217
	v_add_f32_e32 v176, v176, v218
	v_mfma_f32_16x16x32_bf16 v[168:171], v[204:207], v[20:23], v[168:171]
	v_add_f32_e32 v176, v176, v219
	v_cvt_pk_bf16_f32 v65, v218, v219
	v_mfma_f32_16x16x32_bf16 v[172:175], v[204:207], v[52:55], v[172:175]
	v_add_f32_e32 v177, v177, v220
	v_add_f32_e32 v177, v177, v221
	v_mfma_f32_16x16x32_bf16 v[168:171], v[208:211], v[24:27], v[168:171]
	v_cvt_pk_bf16_f32 v96, v220, v221
	v_add_f32_e32 v177, v177, v222
	v_mfma_f32_16x16x32_bf16 v[172:175], v[208:211], v[56:59], v[172:175]
	v_add_f32_e32 v177, v177, v223
	v_cvt_pk_bf16_f32 v97, v222, v223
	v_mfma_f32_16x16x32_bf16 v[168:171], v[212:215], v[28:31], v[168:171]
	v_mfma_f32_16x16x32_bf16 v[172:175], v[212:215], v[60:63], v[172:175]
	s_waitcnt lgkmcnt(0)
	ds_read_b128 v[184:187], v233 offset:25344
	ds_read_b128 v[188:191], v233 offset:25408
	ds_read_b128 v[192:195], v233 offset:25472
	ds_read_b128 v[196:199], v233 offset:25536
	ds_read_b128 v[200:203], v233 offset:25600
	ds_read_b128 v[204:207], v233 offset:25664
	ds_read_b128 v[208:211], v233 offset:25728
	ds_read_b128 v[212:215], v233 offset:25792
	v_mfma_f32_16x16x32_bf16 v[160:163], v[128:131], v[0:3], 0
	v_fma_f32 v216, v168, v178, -v180
	v_fma_f32 v217, v169, v178, -v180
	v_mfma_f32_16x16x32_bf16 v[164:167], v[128:131], v[32:35], 0
	v_fma_f32 v218, v170, v178, -v180
	v_fma_f32 v219, v171, v178, -v180
	v_mfma_f32_16x16x32_bf16 v[160:163], v[132:135], v[4:7], v[160:163]
	v_exp_f32_e32 v216, v216
	v_exp_f32_e32 v217, v217
	v_mfma_f32_16x16x32_bf16 v[164:167], v[132:135], v[36:39], v[164:167]
	v_exp_f32_e32 v218, v218
	v_exp_f32_e32 v219, v219
	v_mfma_f32_16x16x32_bf16 v[160:163], v[136:139], v[8:11], v[160:163]
	v_fma_f32 v220, v172, v179, -v180
	v_fma_f32 v221, v173, v179, -v180
	v_mfma_f32_16x16x32_bf16 v[164:167], v[136:139], v[40:43], v[164:167]
	v_fma_f32 v222, v174, v179, -v180
	v_fma_f32 v223, v175, v179, -v180
	v_mfma_f32_16x16x32_bf16 v[160:163], v[140:143], v[12:15], v[160:163]
	v_exp_f32_e32 v220, v220
	v_exp_f32_e32 v221, v221
	v_mfma_f32_16x16x32_bf16 v[164:167], v[140:143], v[44:47], v[164:167]
	v_exp_f32_e32 v222, v222
	v_exp_f32_e32 v223, v223
	v_mfma_f32_16x16x32_bf16 v[160:163], v[144:147], v[16:19], v[160:163]
	v_add_f32_e32 v176, v176, v216
	v_add_f32_e32 v176, v176, v217
	v_mfma_f32_16x16x32_bf16 v[164:167], v[144:147], v[48:51], v[164:167]
	v_cvt_pk_bf16_f32 v66, v216, v217
	v_add_f32_e32 v176, v176, v218
	v_mfma_f32_16x16x32_bf16 v[160:163], v[148:151], v[20:23], v[160:163]
	v_add_f32_e32 v176, v176, v219
	v_cvt_pk_bf16_f32 v67, v218, v219
	v_mfma_f32_16x16x32_bf16 v[164:167], v[148:151], v[52:55], v[164:167]
	v_add_f32_e32 v177, v177, v220
	v_add_f32_e32 v177, v177, v221
	v_mfma_f32_16x16x32_bf16 v[160:163], v[152:155], v[24:27], v[160:163]
	v_cvt_pk_bf16_f32 v98, v220, v221
	v_add_f32_e32 v177, v177, v222
	v_mfma_f32_16x16x32_bf16 v[164:167], v[152:155], v[56:59], v[164:167]
	v_add_f32_e32 v177, v177, v223
	v_cvt_pk_bf16_f32 v99, v222, v223
	v_mfma_f32_16x16x32_bf16 v[160:163], v[156:159], v[28:31], v[160:163]
	v_mfma_f32_16x16x32_bf16 v[164:167], v[156:159], v[60:63], v[164:167]
	s_waitcnt lgkmcnt(0)
	ds_read_b128 v[128:131], v233 offset:33792
	ds_read_b128 v[132:135], v233 offset:33856
	ds_read_b128 v[136:139], v233 offset:33920
	ds_read_b128 v[140:143], v233 offset:33984
	ds_read_b128 v[144:147], v233 offset:34048
	ds_read_b128 v[148:151], v233 offset:34112
	ds_read_b128 v[152:155], v233 offset:34176
	ds_read_b128 v[156:159], v233 offset:34240
	v_mfma_f32_16x16x32_bf16 v[168:171], v[184:187], v[0:3], 0
	v_fma_f32 v216, v160, v178, -v180
	v_fma_f32 v217, v161, v178, -v180
	v_mfma_f32_16x16x32_bf16 v[172:175], v[184:187], v[32:35], 0
	v_fma_f32 v218, v162, v178, -v180
	v_fma_f32 v219, v163, v178, -v180
	v_mfma_f32_16x16x32_bf16 v[168:171], v[188:191], v[4:7], v[168:171]
	v_exp_f32_e32 v216, v216
	v_exp_f32_e32 v217, v217
	v_mfma_f32_16x16x32_bf16 v[172:175], v[188:191], v[36:39], v[172:175]
	v_exp_f32_e32 v218, v218
	v_exp_f32_e32 v219, v219
	v_mfma_f32_16x16x32_bf16 v[168:171], v[192:195], v[8:11], v[168:171]
	v_fma_f32 v220, v164, v179, -v180
	v_fma_f32 v221, v165, v179, -v180
	v_mfma_f32_16x16x32_bf16 v[172:175], v[192:195], v[40:43], v[172:175]
	v_fma_f32 v222, v166, v179, -v180
	v_fma_f32 v223, v167, v179, -v180
	v_mfma_f32_16x16x32_bf16 v[168:171], v[196:199], v[12:15], v[168:171]
	v_exp_f32_e32 v220, v220
	v_exp_f32_e32 v221, v221
	v_mfma_f32_16x16x32_bf16 v[172:175], v[196:199], v[44:47], v[172:175]
	v_exp_f32_e32 v222, v222
	v_exp_f32_e32 v223, v223
	v_mfma_f32_16x16x32_bf16 v[168:171], v[200:203], v[16:19], v[168:171]
	v_add_f32_e32 v176, v176, v216
	v_add_f32_e32 v176, v176, v217
	v_mfma_f32_16x16x32_bf16 v[172:175], v[200:203], v[48:51], v[172:175]
	v_cvt_pk_bf16_f32 v68, v216, v217
	v_add_f32_e32 v176, v176, v218
	v_mfma_f32_16x16x32_bf16 v[168:171], v[204:207], v[20:23], v[168:171]
	v_add_f32_e32 v176, v176, v219
	v_cvt_pk_bf16_f32 v69, v218, v219
	v_mfma_f32_16x16x32_bf16 v[172:175], v[204:207], v[52:55], v[172:175]
	v_add_f32_e32 v177, v177, v220
	v_add_f32_e32 v177, v177, v221
	v_mfma_f32_16x16x32_bf16 v[168:171], v[208:211], v[24:27], v[168:171]
	v_cvt_pk_bf16_f32 v100, v220, v221
	v_add_f32_e32 v177, v177, v222
	v_mfma_f32_16x16x32_bf16 v[172:175], v[208:211], v[56:59], v[172:175]
	v_add_f32_e32 v177, v177, v223
	v_cvt_pk_bf16_f32 v101, v222, v223
	v_mfma_f32_16x16x32_bf16 v[168:171], v[212:215], v[28:31], v[168:171]
	v_mfma_f32_16x16x32_bf16 v[172:175], v[212:215], v[60:63], v[172:175]
	s_waitcnt lgkmcnt(0)
	ds_read_b128 v[184:187], v233 offset:42240
	ds_read_b128 v[188:191], v233 offset:42304
	ds_read_b128 v[192:195], v233 offset:42368
	ds_read_b128 v[196:199], v233 offset:42432
	ds_read_b128 v[200:203], v233 offset:42496
	ds_read_b128 v[204:207], v233 offset:42560
	ds_read_b128 v[208:211], v233 offset:42624
	ds_read_b128 v[212:215], v233 offset:42688
	v_mfma_f32_16x16x32_bf16 v[160:163], v[128:131], v[0:3], 0
	v_fma_f32 v216, v168, v178, -v180
	v_fma_f32 v217, v169, v178, -v180
	v_mfma_f32_16x16x32_bf16 v[164:167], v[128:131], v[32:35], 0
	v_fma_f32 v218, v170, v178, -v180
	v_fma_f32 v219, v171, v178, -v180
	v_mfma_f32_16x16x32_bf16 v[160:163], v[132:135], v[4:7], v[160:163]
	v_exp_f32_e32 v216, v216
	v_exp_f32_e32 v217, v217
	v_mfma_f32_16x16x32_bf16 v[164:167], v[132:135], v[36:39], v[164:167]
	v_exp_f32_e32 v218, v218
	v_exp_f32_e32 v219, v219
	v_mfma_f32_16x16x32_bf16 v[160:163], v[136:139], v[8:11], v[160:163]
	v_fma_f32 v220, v172, v179, -v180
	v_fma_f32 v221, v173, v179, -v180
	v_mfma_f32_16x16x32_bf16 v[164:167], v[136:139], v[40:43], v[164:167]
	v_fma_f32 v222, v174, v179, -v180
	v_fma_f32 v223, v175, v179, -v180
	v_mfma_f32_16x16x32_bf16 v[160:163], v[140:143], v[12:15], v[160:163]
	v_exp_f32_e32 v220, v220
	v_exp_f32_e32 v221, v221
	v_mfma_f32_16x16x32_bf16 v[164:167], v[140:143], v[44:47], v[164:167]
	v_exp_f32_e32 v222, v222
	v_exp_f32_e32 v223, v223
	v_mfma_f32_16x16x32_bf16 v[160:163], v[144:147], v[16:19], v[160:163]
	v_add_f32_e32 v176, v176, v216
	v_add_f32_e32 v176, v176, v217
	v_mfma_f32_16x16x32_bf16 v[164:167], v[144:147], v[48:51], v[164:167]
	v_cvt_pk_bf16_f32 v70, v216, v217
	v_add_f32_e32 v176, v176, v218
	v_mfma_f32_16x16x32_bf16 v[160:163], v[148:151], v[20:23], v[160:163]
	v_add_f32_e32 v176, v176, v219
	v_cvt_pk_bf16_f32 v71, v218, v219
	v_mfma_f32_16x16x32_bf16 v[164:167], v[148:151], v[52:55], v[164:167]
	v_add_f32_e32 v177, v177, v220
	v_add_f32_e32 v177, v177, v221
	v_mfma_f32_16x16x32_bf16 v[160:163], v[152:155], v[24:27], v[160:163]
	v_cvt_pk_bf16_f32 v102, v220, v221
	v_add_f32_e32 v177, v177, v222
	v_mfma_f32_16x16x32_bf16 v[164:167], v[152:155], v[56:59], v[164:167]
	v_add_f32_e32 v177, v177, v223
	v_cvt_pk_bf16_f32 v103, v222, v223
	v_mfma_f32_16x16x32_bf16 v[160:163], v[156:159], v[28:31], v[160:163]
	v_mfma_f32_16x16x32_bf16 v[164:167], v[156:159], v[60:63], v[164:167]
	s_waitcnt lgkmcnt(0)
	ds_read_b128 v[128:131], v233 offset:50688
	ds_read_b128 v[132:135], v233 offset:50752
	ds_read_b128 v[136:139], v233 offset:50816
	ds_read_b128 v[140:143], v233 offset:50880
	ds_read_b128 v[144:147], v233 offset:50944
	ds_read_b128 v[148:151], v233 offset:51008
	ds_read_b128 v[152:155], v233 offset:51072
	ds_read_b128 v[156:159], v233 offset:51136
	v_mfma_f32_16x16x32_bf16 v[168:171], v[184:187], v[0:3], 0
	v_fma_f32 v216, v160, v178, -v180
	v_fma_f32 v217, v161, v178, -v180
	v_mfma_f32_16x16x32_bf16 v[172:175], v[184:187], v[32:35], 0
	v_fma_f32 v218, v162, v178, -v180
	v_fma_f32 v219, v163, v178, -v180
	v_mfma_f32_16x16x32_bf16 v[168:171], v[188:191], v[4:7], v[168:171]
	v_exp_f32_e32 v216, v216
	v_exp_f32_e32 v217, v217
	v_mfma_f32_16x16x32_bf16 v[172:175], v[188:191], v[36:39], v[172:175]
	v_exp_f32_e32 v218, v218
	v_exp_f32_e32 v219, v219
	v_mfma_f32_16x16x32_bf16 v[168:171], v[192:195], v[8:11], v[168:171]
	v_fma_f32 v220, v164, v179, -v180
	v_fma_f32 v221, v165, v179, -v180
	v_mfma_f32_16x16x32_bf16 v[172:175], v[192:195], v[40:43], v[172:175]
	v_fma_f32 v222, v166, v179, -v180
	v_fma_f32 v223, v167, v179, -v180
	v_mfma_f32_16x16x32_bf16 v[168:171], v[196:199], v[12:15], v[168:171]
	v_exp_f32_e32 v220, v220
	v_exp_f32_e32 v221, v221
	v_mfma_f32_16x16x32_bf16 v[172:175], v[196:199], v[44:47], v[172:175]
	v_exp_f32_e32 v222, v222
	v_exp_f32_e32 v223, v223
	v_mfma_f32_16x16x32_bf16 v[168:171], v[200:203], v[16:19], v[168:171]
	v_add_f32_e32 v176, v176, v216
	v_add_f32_e32 v176, v176, v217
	v_mfma_f32_16x16x32_bf16 v[172:175], v[200:203], v[48:51], v[172:175]
	v_cvt_pk_bf16_f32 v72, v216, v217
	v_add_f32_e32 v176, v176, v218
	v_mfma_f32_16x16x32_bf16 v[168:171], v[204:207], v[20:23], v[168:171]
	v_add_f32_e32 v176, v176, v219
	v_cvt_pk_bf16_f32 v73, v218, v219
	v_mfma_f32_16x16x32_bf16 v[172:175], v[204:207], v[52:55], v[172:175]
	v_add_f32_e32 v177, v177, v220
	v_add_f32_e32 v177, v177, v221
	v_mfma_f32_16x16x32_bf16 v[168:171], v[208:211], v[24:27], v[168:171]
	v_cvt_pk_bf16_f32 v104, v220, v221
	v_add_f32_e32 v177, v177, v222
	v_mfma_f32_16x16x32_bf16 v[172:175], v[208:211], v[56:59], v[172:175]
	v_add_f32_e32 v177, v177, v223
	v_cvt_pk_bf16_f32 v105, v222, v223
	v_mfma_f32_16x16x32_bf16 v[168:171], v[212:215], v[28:31], v[168:171]
	v_mfma_f32_16x16x32_bf16 v[172:175], v[212:215], v[60:63], v[172:175]
	s_waitcnt lgkmcnt(0)
	v_add_u32_e32 v233, 59136, v233
	ds_read_b128 v[184:187], v233 offset:0
	ds_read_b128 v[188:191], v233 offset:64
	ds_read_b128 v[192:195], v233 offset:128
	ds_read_b128 v[196:199], v233 offset:192
	ds_read_b128 v[200:203], v233 offset:256
	ds_read_b128 v[204:207], v233 offset:320
	ds_read_b128 v[208:211], v233 offset:384
	ds_read_b128 v[212:215], v233 offset:448
	v_mfma_f32_16x16x32_bf16 v[160:163], v[128:131], v[0:3], 0
	v_fma_f32 v216, v168, v178, -v180
	v_fma_f32 v217, v169, v178, -v180
	v_mfma_f32_16x16x32_bf16 v[164:167], v[128:131], v[32:35], 0
	v_fma_f32 v218, v170, v178, -v180
	v_fma_f32 v219, v171, v178, -v180
	v_mfma_f32_16x16x32_bf16 v[160:163], v[132:135], v[4:7], v[160:163]
	v_exp_f32_e32 v216, v216
	v_exp_f32_e32 v217, v217
	v_mfma_f32_16x16x32_bf16 v[164:167], v[132:135], v[36:39], v[164:167]
	v_exp_f32_e32 v218, v218
	v_exp_f32_e32 v219, v219
	v_mfma_f32_16x16x32_bf16 v[160:163], v[136:139], v[8:11], v[160:163]
	v_fma_f32 v220, v172, v179, -v180
	v_fma_f32 v221, v173, v179, -v180
	v_mfma_f32_16x16x32_bf16 v[164:167], v[136:139], v[40:43], v[164:167]
	v_fma_f32 v222, v174, v179, -v180
	v_fma_f32 v223, v175, v179, -v180
	v_mfma_f32_16x16x32_bf16 v[160:163], v[140:143], v[12:15], v[160:163]
	v_exp_f32_e32 v220, v220
	v_exp_f32_e32 v221, v221
	v_mfma_f32_16x16x32_bf16 v[164:167], v[140:143], v[44:47], v[164:167]
	v_exp_f32_e32 v222, v222
	v_exp_f32_e32 v223, v223
	v_mfma_f32_16x16x32_bf16 v[160:163], v[144:147], v[16:19], v[160:163]
	v_add_f32_e32 v176, v176, v216
	v_add_f32_e32 v176, v176, v217
	v_mfma_f32_16x16x32_bf16 v[164:167], v[144:147], v[48:51], v[164:167]
	v_cvt_pk_bf16_f32 v74, v216, v217
	v_add_f32_e32 v176, v176, v218
	v_mfma_f32_16x16x32_bf16 v[160:163], v[148:151], v[20:23], v[160:163]
	v_add_f32_e32 v176, v176, v219
	v_cvt_pk_bf16_f32 v75, v218, v219
	v_mfma_f32_16x16x32_bf16 v[164:167], v[148:151], v[52:55], v[164:167]
	v_add_f32_e32 v177, v177, v220
	v_add_f32_e32 v177, v177, v221
	v_mfma_f32_16x16x32_bf16 v[160:163], v[152:155], v[24:27], v[160:163]
	v_cvt_pk_bf16_f32 v106, v220, v221
	v_add_f32_e32 v177, v177, v222
	v_mfma_f32_16x16x32_bf16 v[164:167], v[152:155], v[56:59], v[164:167]
	v_add_f32_e32 v177, v177, v223
	v_cvt_pk_bf16_f32 v107, v222, v223
	v_mfma_f32_16x16x32_bf16 v[160:163], v[156:159], v[28:31], v[160:163]
	v_mfma_f32_16x16x32_bf16 v[164:167], v[156:159], v[60:63], v[164:167]
	s_waitcnt lgkmcnt(0)
	ds_read_b128 v[128:131], v233 offset:8448
	ds_read_b128 v[132:135], v233 offset:8512
	ds_read_b128 v[136:139], v233 offset:8576
	ds_read_b128 v[140:143], v233 offset:8640
	ds_read_b128 v[144:147], v233 offset:8704
	ds_read_b128 v[148:151], v233 offset:8768
	ds_read_b128 v[152:155], v233 offset:8832
	ds_read_b128 v[156:159], v233 offset:8896
	v_mfma_f32_16x16x32_bf16 v[168:171], v[184:187], v[0:3], 0
	v_fma_f32 v216, v160, v178, -v180
	v_fma_f32 v217, v161, v178, -v180
	v_mfma_f32_16x16x32_bf16 v[172:175], v[184:187], v[32:35], 0
	v_fma_f32 v218, v162, v178, -v180
	v_fma_f32 v219, v163, v178, -v180
	v_mfma_f32_16x16x32_bf16 v[168:171], v[188:191], v[4:7], v[168:171]
	v_exp_f32_e32 v216, v216
	v_exp_f32_e32 v217, v217
	v_mfma_f32_16x16x32_bf16 v[172:175], v[188:191], v[36:39], v[172:175]
	v_exp_f32_e32 v218, v218
	v_exp_f32_e32 v219, v219
	v_mfma_f32_16x16x32_bf16 v[168:171], v[192:195], v[8:11], v[168:171]
	v_fma_f32 v220, v164, v179, -v180
	v_fma_f32 v221, v165, v179, -v180
	v_mfma_f32_16x16x32_bf16 v[172:175], v[192:195], v[40:43], v[172:175]
	v_fma_f32 v222, v166, v179, -v180
	v_fma_f32 v223, v167, v179, -v180
	v_mfma_f32_16x16x32_bf16 v[168:171], v[196:199], v[12:15], v[168:171]
	v_exp_f32_e32 v220, v220
	v_exp_f32_e32 v221, v221
	v_mfma_f32_16x16x32_bf16 v[172:175], v[196:199], v[44:47], v[172:175]
	v_exp_f32_e32 v222, v222
	v_exp_f32_e32 v223, v223
	v_mfma_f32_16x16x32_bf16 v[168:171], v[200:203], v[16:19], v[168:171]
	v_add_f32_e32 v176, v176, v216
	v_add_f32_e32 v176, v176, v217
	v_mfma_f32_16x16x32_bf16 v[172:175], v[200:203], v[48:51], v[172:175]
	v_cvt_pk_bf16_f32 v76, v216, v217
	v_add_f32_e32 v176, v176, v218
	v_mfma_f32_16x16x32_bf16 v[168:171], v[204:207], v[20:23], v[168:171]
	v_add_f32_e32 v176, v176, v219
	v_cvt_pk_bf16_f32 v77, v218, v219
	v_mfma_f32_16x16x32_bf16 v[172:175], v[204:207], v[52:55], v[172:175]
	v_add_f32_e32 v177, v177, v220
	v_add_f32_e32 v177, v177, v221
	v_mfma_f32_16x16x32_bf16 v[168:171], v[208:211], v[24:27], v[168:171]
	v_cvt_pk_bf16_f32 v108, v220, v221
	v_add_f32_e32 v177, v177, v222
	v_mfma_f32_16x16x32_bf16 v[172:175], v[208:211], v[56:59], v[172:175]
	v_add_f32_e32 v177, v177, v223
	v_cvt_pk_bf16_f32 v109, v222, v223
	v_mfma_f32_16x16x32_bf16 v[168:171], v[212:215], v[28:31], v[168:171]
	v_mfma_f32_16x16x32_bf16 v[172:175], v[212:215], v[60:63], v[172:175]
	s_waitcnt lgkmcnt(0)
	ds_read_b128 v[184:187], v233 offset:16896
	ds_read_b128 v[188:191], v233 offset:16960
	ds_read_b128 v[192:195], v233 offset:17024
	ds_read_b128 v[196:199], v233 offset:17088
	ds_read_b128 v[200:203], v233 offset:17152
	ds_read_b128 v[204:207], v233 offset:17216
	ds_read_b128 v[208:211], v233 offset:17280
	ds_read_b128 v[212:215], v233 offset:17344
	v_mfma_f32_16x16x32_bf16 v[160:163], v[128:131], v[0:3], 0
	v_fma_f32 v216, v168, v178, -v180
	v_fma_f32 v217, v169, v178, -v180
	v_mfma_f32_16x16x32_bf16 v[164:167], v[128:131], v[32:35], 0
	v_fma_f32 v218, v170, v178, -v180
	v_fma_f32 v219, v171, v178, -v180
	v_mfma_f32_16x16x32_bf16 v[160:163], v[132:135], v[4:7], v[160:163]
	v_exp_f32_e32 v216, v216
	v_exp_f32_e32 v217, v217
	v_mfma_f32_16x16x32_bf16 v[164:167], v[132:135], v[36:39], v[164:167]
	v_exp_f32_e32 v218, v218
	v_exp_f32_e32 v219, v219
	v_mfma_f32_16x16x32_bf16 v[160:163], v[136:139], v[8:11], v[160:163]
	v_fma_f32 v220, v172, v179, -v180
	v_fma_f32 v221, v173, v179, -v180
	v_mfma_f32_16x16x32_bf16 v[164:167], v[136:139], v[40:43], v[164:167]
	v_fma_f32 v222, v174, v179, -v180
	v_fma_f32 v223, v175, v179, -v180
	v_mfma_f32_16x16x32_bf16 v[160:163], v[140:143], v[12:15], v[160:163]
	v_exp_f32_e32 v220, v220
	v_exp_f32_e32 v221, v221
	v_mfma_f32_16x16x32_bf16 v[164:167], v[140:143], v[44:47], v[164:167]
	v_exp_f32_e32 v222, v222
	v_exp_f32_e32 v223, v223
	v_mfma_f32_16x16x32_bf16 v[160:163], v[144:147], v[16:19], v[160:163]
	v_add_f32_e32 v176, v176, v216
	v_add_f32_e32 v176, v176, v217
	v_mfma_f32_16x16x32_bf16 v[164:167], v[144:147], v[48:51], v[164:167]
	v_cvt_pk_bf16_f32 v78, v216, v217
	v_add_f32_e32 v176, v176, v218
	v_mfma_f32_16x16x32_bf16 v[160:163], v[148:151], v[20:23], v[160:163]
	v_add_f32_e32 v176, v176, v219
	v_cvt_pk_bf16_f32 v79, v218, v219
	v_mfma_f32_16x16x32_bf16 v[164:167], v[148:151], v[52:55], v[164:167]
	v_add_f32_e32 v177, v177, v220
	v_add_f32_e32 v177, v177, v221
	v_mfma_f32_16x16x32_bf16 v[160:163], v[152:155], v[24:27], v[160:163]
	v_cvt_pk_bf16_f32 v110, v220, v221
	v_add_f32_e32 v177, v177, v222
	v_mfma_f32_16x16x32_bf16 v[164:167], v[152:155], v[56:59], v[164:167]
	v_add_f32_e32 v177, v177, v223
	v_cvt_pk_bf16_f32 v111, v222, v223
	v_mfma_f32_16x16x32_bf16 v[160:163], v[156:159], v[28:31], v[160:163]
	v_mfma_f32_16x16x32_bf16 v[164:167], v[156:159], v[60:63], v[164:167]
	s_waitcnt lgkmcnt(0)
	ds_read_b128 v[128:131], v233 offset:25344
	ds_read_b128 v[132:135], v233 offset:25408
	ds_read_b128 v[136:139], v233 offset:25472
	ds_read_b128 v[140:143], v233 offset:25536
	ds_read_b128 v[144:147], v233 offset:25600
	ds_read_b128 v[148:151], v233 offset:25664
	ds_read_b128 v[152:155], v233 offset:25728
	ds_read_b128 v[156:159], v233 offset:25792
	v_mfma_f32_16x16x32_bf16 v[168:171], v[184:187], v[0:3], 0
	v_fma_f32 v216, v160, v178, -v180
	v_fma_f32 v217, v161, v178, -v180
	v_mfma_f32_16x16x32_bf16 v[172:175], v[184:187], v[32:35], 0
	v_fma_f32 v218, v162, v178, -v180
	v_fma_f32 v219, v163, v178, -v180
	v_mfma_f32_16x16x32_bf16 v[168:171], v[188:191], v[4:7], v[168:171]
	v_exp_f32_e32 v216, v216
	v_exp_f32_e32 v217, v217
	v_mfma_f32_16x16x32_bf16 v[172:175], v[188:191], v[36:39], v[172:175]
	v_exp_f32_e32 v218, v218
	v_exp_f32_e32 v219, v219
	v_mfma_f32_16x16x32_bf16 v[168:171], v[192:195], v[8:11], v[168:171]
	v_fma_f32 v220, v164, v179, -v180
	v_fma_f32 v221, v165, v179, -v180
	v_mfma_f32_16x16x32_bf16 v[172:175], v[192:195], v[40:43], v[172:175]
	v_fma_f32 v222, v166, v179, -v180
	v_fma_f32 v223, v167, v179, -v180
	v_mfma_f32_16x16x32_bf16 v[168:171], v[196:199], v[12:15], v[168:171]
	v_exp_f32_e32 v220, v220
	v_exp_f32_e32 v221, v221
	v_mfma_f32_16x16x32_bf16 v[172:175], v[196:199], v[44:47], v[172:175]
	v_exp_f32_e32 v222, v222
	v_exp_f32_e32 v223, v223
	v_mfma_f32_16x16x32_bf16 v[168:171], v[200:203], v[16:19], v[168:171]
	v_add_f32_e32 v176, v176, v216
	v_add_f32_e32 v176, v176, v217
	v_mfma_f32_16x16x32_bf16 v[172:175], v[200:203], v[48:51], v[172:175]
	v_cvt_pk_bf16_f32 v80, v216, v217
	v_add_f32_e32 v176, v176, v218
	v_mfma_f32_16x16x32_bf16 v[168:171], v[204:207], v[20:23], v[168:171]
	v_add_f32_e32 v176, v176, v219
	v_cvt_pk_bf16_f32 v81, v218, v219
	v_mfma_f32_16x16x32_bf16 v[172:175], v[204:207], v[52:55], v[172:175]
	v_add_f32_e32 v177, v177, v220
	v_add_f32_e32 v177, v177, v221
	v_mfma_f32_16x16x32_bf16 v[168:171], v[208:211], v[24:27], v[168:171]
	v_cvt_pk_bf16_f32 v112, v220, v221
	v_add_f32_e32 v177, v177, v222
	v_mfma_f32_16x16x32_bf16 v[172:175], v[208:211], v[56:59], v[172:175]
	v_add_f32_e32 v177, v177, v223
	v_cvt_pk_bf16_f32 v113, v222, v223
	v_mfma_f32_16x16x32_bf16 v[168:171], v[212:215], v[28:31], v[168:171]
	v_mfma_f32_16x16x32_bf16 v[172:175], v[212:215], v[60:63], v[172:175]
	s_waitcnt lgkmcnt(0)
	ds_read_b128 v[184:187], v233 offset:33792
	ds_read_b128 v[188:191], v233 offset:33856
	ds_read_b128 v[192:195], v233 offset:33920
	ds_read_b128 v[196:199], v233 offset:33984
	ds_read_b128 v[200:203], v233 offset:34048
	ds_read_b128 v[204:207], v233 offset:34112
	ds_read_b128 v[208:211], v233 offset:34176
	ds_read_b128 v[212:215], v233 offset:34240
	v_mfma_f32_16x16x32_bf16 v[160:163], v[128:131], v[0:3], 0
	v_fma_f32 v216, v168, v178, -v180
	v_fma_f32 v217, v169, v178, -v180
	v_mfma_f32_16x16x32_bf16 v[164:167], v[128:131], v[32:35], 0
	v_fma_f32 v218, v170, v178, -v180
	v_fma_f32 v219, v171, v178, -v180
	v_mfma_f32_16x16x32_bf16 v[160:163], v[132:135], v[4:7], v[160:163]
	v_exp_f32_e32 v216, v216
	v_exp_f32_e32 v217, v217
	v_mfma_f32_16x16x32_bf16 v[164:167], v[132:135], v[36:39], v[164:167]
	v_exp_f32_e32 v218, v218
	v_exp_f32_e32 v219, v219
	v_mfma_f32_16x16x32_bf16 v[160:163], v[136:139], v[8:11], v[160:163]
	v_fma_f32 v220, v172, v179, -v180
	v_fma_f32 v221, v173, v179, -v180
	v_mfma_f32_16x16x32_bf16 v[164:167], v[136:139], v[40:43], v[164:167]
	v_fma_f32 v222, v174, v179, -v180
	v_fma_f32 v223, v175, v179, -v180
	v_mfma_f32_16x16x32_bf16 v[160:163], v[140:143], v[12:15], v[160:163]
	v_exp_f32_e32 v220, v220
	v_exp_f32_e32 v221, v221
	v_mfma_f32_16x16x32_bf16 v[164:167], v[140:143], v[44:47], v[164:167]
	v_exp_f32_e32 v222, v222
	v_exp_f32_e32 v223, v223
	v_mfma_f32_16x16x32_bf16 v[160:163], v[144:147], v[16:19], v[160:163]
	v_add_f32_e32 v176, v176, v216
	v_add_f32_e32 v176, v176, v217
	v_mfma_f32_16x16x32_bf16 v[164:167], v[144:147], v[48:51], v[164:167]
	v_cvt_pk_bf16_f32 v82, v216, v217
	v_add_f32_e32 v176, v176, v218
	v_mfma_f32_16x16x32_bf16 v[160:163], v[148:151], v[20:23], v[160:163]
	v_add_f32_e32 v176, v176, v219
	v_cvt_pk_bf16_f32 v83, v218, v219
	v_mfma_f32_16x16x32_bf16 v[164:167], v[148:151], v[52:55], v[164:167]
	v_add_f32_e32 v177, v177, v220
	v_add_f32_e32 v177, v177, v221
	v_mfma_f32_16x16x32_bf16 v[160:163], v[152:155], v[24:27], v[160:163]
	v_cvt_pk_bf16_f32 v114, v220, v221
	v_add_f32_e32 v177, v177, v222
	v_mfma_f32_16x16x32_bf16 v[164:167], v[152:155], v[56:59], v[164:167]
	v_add_f32_e32 v177, v177, v223
	v_cvt_pk_bf16_f32 v115, v222, v223
	v_mfma_f32_16x16x32_bf16 v[160:163], v[156:159], v[28:31], v[160:163]
	v_mfma_f32_16x16x32_bf16 v[164:167], v[156:159], v[60:63], v[164:167]
	s_waitcnt lgkmcnt(0)
	ds_read_b128 v[128:131], v233 offset:42240
	ds_read_b128 v[132:135], v233 offset:42304
	ds_read_b128 v[136:139], v233 offset:42368
	ds_read_b128 v[140:143], v233 offset:42432
	ds_read_b128 v[144:147], v233 offset:42496
	ds_read_b128 v[148:151], v233 offset:42560
	ds_read_b128 v[152:155], v233 offset:42624
	ds_read_b128 v[156:159], v233 offset:42688
	v_mfma_f32_16x16x32_bf16 v[168:171], v[184:187], v[0:3], 0
	v_fma_f32 v216, v160, v178, -v180
	v_fma_f32 v217, v161, v178, -v180
	v_mfma_f32_16x16x32_bf16 v[172:175], v[184:187], v[32:35], 0
	v_fma_f32 v218, v162, v178, -v180
	v_fma_f32 v219, v163, v178, -v180
	v_mfma_f32_16x16x32_bf16 v[168:171], v[188:191], v[4:7], v[168:171]
	v_exp_f32_e32 v216, v216
	v_exp_f32_e32 v217, v217
	v_mfma_f32_16x16x32_bf16 v[172:175], v[188:191], v[36:39], v[172:175]
	v_exp_f32_e32 v218, v218
	v_exp_f32_e32 v219, v219
	v_mfma_f32_16x16x32_bf16 v[168:171], v[192:195], v[8:11], v[168:171]
	v_fma_f32 v220, v164, v179, -v180
	v_fma_f32 v221, v165, v179, -v180
	v_mfma_f32_16x16x32_bf16 v[172:175], v[192:195], v[40:43], v[172:175]
	v_fma_f32 v222, v166, v179, -v180
	v_fma_f32 v223, v167, v179, -v180
	v_mfma_f32_16x16x32_bf16 v[168:171], v[196:199], v[12:15], v[168:171]
	v_exp_f32_e32 v220, v220
	v_exp_f32_e32 v221, v221
	v_mfma_f32_16x16x32_bf16 v[172:175], v[196:199], v[44:47], v[172:175]
	v_exp_f32_e32 v222, v222
	v_exp_f32_e32 v223, v223
	v_mfma_f32_16x16x32_bf16 v[168:171], v[200:203], v[16:19], v[168:171]
	v_add_f32_e32 v176, v176, v216
	v_add_f32_e32 v176, v176, v217
	v_mfma_f32_16x16x32_bf16 v[172:175], v[200:203], v[48:51], v[172:175]
	v_cvt_pk_bf16_f32 v84, v216, v217
	v_add_f32_e32 v176, v176, v218
	v_mfma_f32_16x16x32_bf16 v[168:171], v[204:207], v[20:23], v[168:171]
	v_add_f32_e32 v176, v176, v219
	v_cvt_pk_bf16_f32 v85, v218, v219
	v_mfma_f32_16x16x32_bf16 v[172:175], v[204:207], v[52:55], v[172:175]
	v_add_f32_e32 v177, v177, v220
	v_add_f32_e32 v177, v177, v221
	v_mfma_f32_16x16x32_bf16 v[168:171], v[208:211], v[24:27], v[168:171]
	v_cvt_pk_bf16_f32 v116, v220, v221
	v_add_f32_e32 v177, v177, v222
	v_mfma_f32_16x16x32_bf16 v[172:175], v[208:211], v[56:59], v[172:175]
	v_add_f32_e32 v177, v177, v223
	v_cvt_pk_bf16_f32 v117, v222, v223
	v_mfma_f32_16x16x32_bf16 v[168:171], v[212:215], v[28:31], v[168:171]
	v_mfma_f32_16x16x32_bf16 v[172:175], v[212:215], v[60:63], v[172:175]
	s_waitcnt lgkmcnt(0)
	ds_read_b128 v[184:187], v233 offset:50688
	ds_read_b128 v[188:191], v233 offset:50752
	ds_read_b128 v[192:195], v233 offset:50816
	ds_read_b128 v[196:199], v233 offset:50880
	ds_read_b128 v[200:203], v233 offset:50944
	ds_read_b128 v[204:207], v233 offset:51008
	ds_read_b128 v[208:211], v233 offset:51072
	ds_read_b128 v[212:215], v233 offset:51136
	v_mfma_f32_16x16x32_bf16 v[160:163], v[128:131], v[0:3], 0
	v_fma_f32 v216, v168, v178, -v180
	v_fma_f32 v217, v169, v178, -v180
	v_mfma_f32_16x16x32_bf16 v[164:167], v[128:131], v[32:35], 0
	v_fma_f32 v218, v170, v178, -v180
	v_fma_f32 v219, v171, v178, -v180
	v_mfma_f32_16x16x32_bf16 v[160:163], v[132:135], v[4:7], v[160:163]
	v_exp_f32_e32 v216, v216
	v_exp_f32_e32 v217, v217
	v_mfma_f32_16x16x32_bf16 v[164:167], v[132:135], v[36:39], v[164:167]
	v_exp_f32_e32 v218, v218
	v_exp_f32_e32 v219, v219
	v_mfma_f32_16x16x32_bf16 v[160:163], v[136:139], v[8:11], v[160:163]
	v_fma_f32 v220, v172, v179, -v180
	v_fma_f32 v221, v173, v179, -v180
	v_mfma_f32_16x16x32_bf16 v[164:167], v[136:139], v[40:43], v[164:167]
	v_fma_f32 v222, v174, v179, -v180
	v_fma_f32 v223, v175, v179, -v180
	v_mfma_f32_16x16x32_bf16 v[160:163], v[140:143], v[12:15], v[160:163]
	v_exp_f32_e32 v220, v220
	v_exp_f32_e32 v221, v221
	v_mfma_f32_16x16x32_bf16 v[164:167], v[140:143], v[44:47], v[164:167]
	v_exp_f32_e32 v222, v222
	v_exp_f32_e32 v223, v223
	v_mfma_f32_16x16x32_bf16 v[160:163], v[144:147], v[16:19], v[160:163]
	v_add_f32_e32 v176, v176, v216
	v_add_f32_e32 v176, v176, v217
	v_mfma_f32_16x16x32_bf16 v[164:167], v[144:147], v[48:51], v[164:167]
	v_cvt_pk_bf16_f32 v86, v216, v217
	v_add_f32_e32 v176, v176, v218
	v_mfma_f32_16x16x32_bf16 v[160:163], v[148:151], v[20:23], v[160:163]
	v_add_f32_e32 v176, v176, v219
	v_cvt_pk_bf16_f32 v87, v218, v219
	v_mfma_f32_16x16x32_bf16 v[164:167], v[148:151], v[52:55], v[164:167]
	v_add_f32_e32 v177, v177, v220
	v_add_f32_e32 v177, v177, v221
	v_mfma_f32_16x16x32_bf16 v[160:163], v[152:155], v[24:27], v[160:163]
	v_cvt_pk_bf16_f32 v118, v220, v221
	v_add_f32_e32 v177, v177, v222
	v_mfma_f32_16x16x32_bf16 v[164:167], v[152:155], v[56:59], v[164:167]
	v_add_f32_e32 v177, v177, v223
	v_cvt_pk_bf16_f32 v119, v222, v223
	v_mfma_f32_16x16x32_bf16 v[160:163], v[156:159], v[28:31], v[160:163]
	v_mfma_f32_16x16x32_bf16 v[164:167], v[156:159], v[60:63], v[164:167]
	s_waitcnt lgkmcnt(0)
	v_add_u32_e32 v233, 59136, v233
	ds_read_b128 v[128:131], v233 offset:0
	ds_read_b128 v[132:135], v233 offset:64
	ds_read_b128 v[136:139], v233 offset:128
	ds_read_b128 v[140:143], v233 offset:192
	ds_read_b128 v[144:147], v233 offset:256
	ds_read_b128 v[148:151], v233 offset:320
	ds_read_b128 v[152:155], v233 offset:384
	ds_read_b128 v[156:159], v233 offset:448
	v_mfma_f32_16x16x32_bf16 v[168:171], v[184:187], v[0:3], 0
	v_fma_f32 v216, v160, v178, -v180
	v_fma_f32 v217, v161, v178, -v180
	v_mfma_f32_16x16x32_bf16 v[172:175], v[184:187], v[32:35], 0
	v_fma_f32 v218, v162, v178, -v180
	v_fma_f32 v219, v163, v178, -v180
	v_mfma_f32_16x16x32_bf16 v[168:171], v[188:191], v[4:7], v[168:171]
	v_exp_f32_e32 v216, v216
	v_exp_f32_e32 v217, v217
	v_mfma_f32_16x16x32_bf16 v[172:175], v[188:191], v[36:39], v[172:175]
	v_exp_f32_e32 v218, v218
	v_exp_f32_e32 v219, v219
	v_mfma_f32_16x16x32_bf16 v[168:171], v[192:195], v[8:11], v[168:171]
	v_fma_f32 v220, v164, v179, -v180
	v_fma_f32 v221, v165, v179, -v180
	v_mfma_f32_16x16x32_bf16 v[172:175], v[192:195], v[40:43], v[172:175]
	v_fma_f32 v222, v166, v179, -v180
	v_fma_f32 v223, v167, v179, -v180
	v_mfma_f32_16x16x32_bf16 v[168:171], v[196:199], v[12:15], v[168:171]
	v_exp_f32_e32 v220, v220
	v_exp_f32_e32 v221, v221
	v_mfma_f32_16x16x32_bf16 v[172:175], v[196:199], v[44:47], v[172:175]
	v_exp_f32_e32 v222, v222
	v_exp_f32_e32 v223, v223
	v_mfma_f32_16x16x32_bf16 v[168:171], v[200:203], v[16:19], v[168:171]
	v_add_f32_e32 v176, v176, v216
	v_add_f32_e32 v176, v176, v217
	v_mfma_f32_16x16x32_bf16 v[172:175], v[200:203], v[48:51], v[172:175]
	v_cvt_pk_bf16_f32 v88, v216, v217
	v_add_f32_e32 v176, v176, v218
	v_mfma_f32_16x16x32_bf16 v[168:171], v[204:207], v[20:23], v[168:171]
	v_add_f32_e32 v176, v176, v219
	v_cvt_pk_bf16_f32 v89, v218, v219
	v_mfma_f32_16x16x32_bf16 v[172:175], v[204:207], v[52:55], v[172:175]
	v_add_f32_e32 v177, v177, v220
	v_add_f32_e32 v177, v177, v221
	v_mfma_f32_16x16x32_bf16 v[168:171], v[208:211], v[24:27], v[168:171]
	v_cvt_pk_bf16_f32 v120, v220, v221
	v_add_f32_e32 v177, v177, v222
	v_mfma_f32_16x16x32_bf16 v[172:175], v[208:211], v[56:59], v[172:175]
	v_add_f32_e32 v177, v177, v223
	v_cvt_pk_bf16_f32 v121, v222, v223
	v_mfma_f32_16x16x32_bf16 v[168:171], v[212:215], v[28:31], v[168:171]
	v_mfma_f32_16x16x32_bf16 v[172:175], v[212:215], v[60:63], v[172:175]
	s_waitcnt lgkmcnt(0)
	ds_read_b128 v[184:187], v233 offset:8448
	ds_read_b128 v[188:191], v233 offset:8512
	ds_read_b128 v[192:195], v233 offset:8576
	ds_read_b128 v[196:199], v233 offset:8640
	ds_read_b128 v[200:203], v233 offset:8704
	ds_read_b128 v[204:207], v233 offset:8768
	ds_read_b128 v[208:211], v233 offset:8832
	ds_read_b128 v[212:215], v233 offset:8896
	v_mfma_f32_16x16x32_bf16 v[160:163], v[128:131], v[0:3], 0
	v_fma_f32 v216, v168, v178, -v180
	v_fma_f32 v217, v169, v178, -v180
	v_mfma_f32_16x16x32_bf16 v[164:167], v[128:131], v[32:35], 0
	v_fma_f32 v218, v170, v178, -v180
	v_fma_f32 v219, v171, v178, -v180
	v_mfma_f32_16x16x32_bf16 v[160:163], v[132:135], v[4:7], v[160:163]
	v_exp_f32_e32 v216, v216
	v_exp_f32_e32 v217, v217
	v_mfma_f32_16x16x32_bf16 v[164:167], v[132:135], v[36:39], v[164:167]
	v_exp_f32_e32 v218, v218
	v_exp_f32_e32 v219, v219
	v_mfma_f32_16x16x32_bf16 v[160:163], v[136:139], v[8:11], v[160:163]
	v_fma_f32 v220, v172, v179, -v180
	v_fma_f32 v221, v173, v179, -v180
	v_mfma_f32_16x16x32_bf16 v[164:167], v[136:139], v[40:43], v[164:167]
	v_fma_f32 v222, v174, v179, -v180
	v_fma_f32 v223, v175, v179, -v180
	v_mfma_f32_16x16x32_bf16 v[160:163], v[140:143], v[12:15], v[160:163]
	v_exp_f32_e32 v220, v220
	v_exp_f32_e32 v221, v221
	v_mfma_f32_16x16x32_bf16 v[164:167], v[140:143], v[44:47], v[164:167]
	v_exp_f32_e32 v222, v222
	v_exp_f32_e32 v223, v223
	v_mfma_f32_16x16x32_bf16 v[160:163], v[144:147], v[16:19], v[160:163]
	v_add_f32_e32 v176, v176, v216
	v_add_f32_e32 v176, v176, v217
	v_mfma_f32_16x16x32_bf16 v[164:167], v[144:147], v[48:51], v[164:167]
	v_cvt_pk_bf16_f32 v90, v216, v217
	v_add_f32_e32 v176, v176, v218
	v_mfma_f32_16x16x32_bf16 v[160:163], v[148:151], v[20:23], v[160:163]
	v_add_f32_e32 v176, v176, v219
	v_cvt_pk_bf16_f32 v91, v218, v219
	v_mfma_f32_16x16x32_bf16 v[164:167], v[148:151], v[52:55], v[164:167]
	v_add_f32_e32 v177, v177, v220
	v_add_f32_e32 v177, v177, v221
	v_mfma_f32_16x16x32_bf16 v[160:163], v[152:155], v[24:27], v[160:163]
	v_cvt_pk_bf16_f32 v122, v220, v221
	v_add_f32_e32 v177, v177, v222
	v_mfma_f32_16x16x32_bf16 v[164:167], v[152:155], v[56:59], v[164:167]
	v_add_f32_e32 v177, v177, v223
	v_cvt_pk_bf16_f32 v123, v222, v223
	v_mfma_f32_16x16x32_bf16 v[160:163], v[156:159], v[28:31], v[160:163]
	v_mfma_f32_16x16x32_bf16 v[164:167], v[156:159], v[60:63], v[164:167]
	s_waitcnt lgkmcnt(0)
	s_nop 6
	v_mfma_f32_16x16x32_bf16 v[168:171], v[184:187], v[0:3], 0
	v_fma_f32 v216, v160, v178, -v180
	v_fma_f32 v217, v161, v178, -v180
	v_mfma_f32_16x16x32_bf16 v[172:175], v[184:187], v[32:35], 0
	v_fma_f32 v218, v162, v178, -v180
	v_fma_f32 v219, v163, v178, -v180
	v_mfma_f32_16x16x32_bf16 v[168:171], v[188:191], v[4:7], v[168:171]
	v_exp_f32_e32 v216, v216
	v_exp_f32_e32 v217, v217
	v_mfma_f32_16x16x32_bf16 v[172:175], v[188:191], v[36:39], v[172:175]
	v_exp_f32_e32 v218, v218
	v_exp_f32_e32 v219, v219
	v_mfma_f32_16x16x32_bf16 v[168:171], v[192:195], v[8:11], v[168:171]
	v_fma_f32 v220, v164, v179, -v180
	v_fma_f32 v221, v165, v179, -v180
	v_mfma_f32_16x16x32_bf16 v[172:175], v[192:195], v[40:43], v[172:175]
	v_fma_f32 v222, v166, v179, -v180
	v_fma_f32 v223, v167, v179, -v180
	v_mfma_f32_16x16x32_bf16 v[168:171], v[196:199], v[12:15], v[168:171]
	v_exp_f32_e32 v220, v220
	v_exp_f32_e32 v221, v221
	v_mfma_f32_16x16x32_bf16 v[172:175], v[196:199], v[44:47], v[172:175]
	v_exp_f32_e32 v222, v222
	v_exp_f32_e32 v223, v223
	v_mfma_f32_16x16x32_bf16 v[168:171], v[200:203], v[16:19], v[168:171]
	v_add_f32_e32 v176, v176, v216
	v_add_f32_e32 v176, v176, v217
	v_mfma_f32_16x16x32_bf16 v[172:175], v[200:203], v[48:51], v[172:175]
	v_cvt_pk_bf16_f32 v92, v216, v217
	v_add_f32_e32 v176, v176, v218
	v_mfma_f32_16x16x32_bf16 v[168:171], v[204:207], v[20:23], v[168:171]
	v_add_f32_e32 v176, v176, v219
	v_cvt_pk_bf16_f32 v93, v218, v219
	v_mfma_f32_16x16x32_bf16 v[172:175], v[204:207], v[52:55], v[172:175]
	v_add_f32_e32 v177, v177, v220
	v_add_f32_e32 v177, v177, v221
	v_mfma_f32_16x16x32_bf16 v[168:171], v[208:211], v[24:27], v[168:171]
	v_cvt_pk_bf16_f32 v124, v220, v221
	v_add_f32_e32 v177, v177, v222
	v_mfma_f32_16x16x32_bf16 v[172:175], v[208:211], v[56:59], v[172:175]
	v_add_f32_e32 v177, v177, v223
	v_cvt_pk_bf16_f32 v125, v222, v223
	v_mfma_f32_16x16x32_bf16 v[168:171], v[212:215], v[28:31], v[168:171]
	v_mfma_f32_16x16x32_bf16 v[172:175], v[212:215], v[60:63], v[172:175]
	s_nop 7
	v_fma_f32 v216, v168, v178, -v180
	v_fma_f32 v217, v169, v178, -v180
	v_fma_f32 v218, v170, v178, -v180
	v_fma_f32 v219, v171, v178, -v180
	v_exp_f32_e32 v216, v216
	v_exp_f32_e32 v217, v217
	v_exp_f32_e32 v218, v218
	v_exp_f32_e32 v219, v219
	v_fma_f32 v220, v172, v179, -v180
	v_fma_f32 v221, v173, v179, -v180
	v_fma_f32 v222, v174, v179, -v180
	v_fma_f32 v223, v175, v179, -v180
	v_exp_f32_e32 v220, v220
	v_exp_f32_e32 v221, v221
	v_exp_f32_e32 v222, v222
	v_exp_f32_e32 v223, v223
	v_add_f32_e32 v176, v176, v216
	v_add_f32_e32 v176, v176, v217
	v_cvt_pk_bf16_f32 v94, v216, v217
	v_add_f32_e32 v176, v176, v218
	v_add_f32_e32 v176, v176, v219
	v_cvt_pk_bf16_f32 v95, v218, v219
	v_add_f32_e32 v177, v177, v220
	v_add_f32_e32 v177, v177, v221
	v_cvt_pk_bf16_f32 v126, v220, v221
	v_add_f32_e32 v177, v177, v222
	v_add_f32_e32 v177, v177, v223
	v_cvt_pk_bf16_f32 v127, v222, v223
	s_barrier
	global_load_dwordx4 v[128:131], v225, s[8:9]
	s_add_u32 s8, s8, 0x14000
	s_addc_u32 s9, s9, 0
	global_load_dwordx4 v[132:135], v225, s[8:9]
	s_add_u32 s8, s8, 0x14000
	s_addc_u32 s9, s9, 0
	global_load_dwordx4 v[136:139], v225, s[8:9]
	s_add_u32 s8, s8, 0x14000
	s_addc_u32 s9, s9, 0
	global_load_dwordx4 v[140:143], v225, s[8:9]
	s_add_u32 s8, s8, 0x14000
	s_addc_u32 s9, s9, 0
	global_load_dwordx4 v[144:147], v225, s[8:9]
	s_add_u32 s8, s8, 0x14000
	s_addc_u32 s9, s9, 0
	global_load_dwordx4 v[148:151], v225, s[8:9]
	s_add_u32 s8, s8, 0x14000
	s_addc_u32 s9, s9, 0
	global_load_dwordx4 v[152:155], v225, s[8:9]
	s_add_u32 s8, s8, 0x14000
	s_addc_u32 s9, s9, 0
	global_load_dwordx4 v[156:159], v225, s[8:9]
	s_add_u32 s8, s8, 0x14000
	s_addc_u32 s9, s9, 0
	global_load_dwordx4 v[184:187], v225, s[8:9]
	s_add_u32 s8, s8, 0x14000
	s_addc_u32 s9, s9, 0
	global_load_dwordx4 v[188:191], v225, s[8:9]
	s_add_u32 s8, s8, 0x14000
	s_addc_u32 s9, s9, 0
	global_load_dwordx4 v[192:195], v225, s[8:9]
	s_add_u32 s8, s8, 0x14000
	s_addc_u32 s9, s9, 0
	global_load_dwordx4 v[196:199], v225, s[8:9]
	s_add_u32 s8, s8, 0x14000
	s_addc_u32 s9, s9, 0
	global_load_dwordx4 v[200:203], v225, s[8:9]
	s_add_u32 s8, s8, 0x14000
	s_addc_u32 s9, s9, 0
	global_load_dwordx4 v[204:207], v225, s[8:9]
	s_add_u32 s8, s8, 0x14000
	s_addc_u32 s9, s9, 0
	global_load_dwordx4 v[208:211], v225, s[8:9]
	s_add_u32 s8, s8, 0x14000
	s_addc_u32 s9, s9, 0
	global_load_dwordx4 v[212:215], v225, s[8:9]
	s_add_i32 s16, s69, s86
	s_cmpk_lt_i32 s16, 0x300
	s_cselect_b32 s16, s16, s69
	s_and_b32 s0, s16, 31
	s_lshr_b32 s1, s16, 8
	s_lshl_b32 s1, s1, 5
	s_add_i32 s1, s1, s0
	s_mul_i32 s0, s1, 2731
	s_lshr_b32 s0, s0, 16
	s_mul_i32 s17, s0, 24
	s_sub_i32 s1, s1, s17
	s_bfe_u32 s17, s16, 0x30005
	s_mul_i32 s17, s17, 24
	s_add_i32 s1, s1, s17
	s_lshl_b32 s11, s1, 19
	s_lshl_b32 s12, s0, 9
	s_add_u32 s11, s11, s12
	s_add_u32 s12, s11, 0xf000000
	s_add_u32 s10, s4, s12
	s_addc_u32 s11, s5, 0
	s_lshl_b32 s12, s1, 12
	s_lshl_b32 s13, s0, 2
	s_add_u32 s12, s12, s13
	s_add_u32 s12, s12, 0x1fa60000
	s_add_u32 s12, s4, s12
	s_addc_u32 s13, s5, 0
	global_load_dwordx4 v[0:3], v228, s[10:11] offset:0
	global_load_dwordx4 v[4:7], v228, s[10:11] offset:64
	global_load_dwordx4 v[8:11], v228, s[10:11] offset:128
	global_load_dwordx4 v[12:15], v228, s[10:11] offset:192
	global_load_dwordx4 v[16:19], v228, s[10:11] offset:256
	global_load_dwordx4 v[20:23], v228, s[10:11] offset:320
	global_load_dwordx4 v[24:27], v228, s[10:11] offset:384
	global_load_dwordx4 v[28:31], v228, s[10:11] offset:448
	global_load_dwordx4 v[32:35], v229, s[10:11] offset:0
	global_load_dwordx4 v[36:39], v229, s[10:11] offset:64
	global_load_dwordx4 v[40:43], v229, s[10:11] offset:128
	global_load_dwordx4 v[44:47], v229, s[10:11] offset:192
	global_load_dwordx4 v[48:51], v229, s[10:11] offset:256
	global_load_dwordx4 v[52:55], v229, s[10:11] offset:320
	global_load_dwordx4 v[56:59], v229, s[10:11] offset:384
	global_load_dwordx4 v[60:63], v229, s[10:11] offset:448
	global_load_dword v247, v230, s[12:13]
	global_load_dword v248, v230, s[12:13] offset:2048
	ds_bpermute_b32 v242, v236, v176
	s_waitcnt lgkmcnt(0)
	v_add_f32_e32 v176, v176, v242
	ds_bpermute_b32 v242, v237, v176
	s_waitcnt lgkmcnt(0)
	v_add_f32_e32 v176, v176, v242
	ds_bpermute_b32 v242, v236, v177
	s_waitcnt lgkmcnt(0)
	v_add_f32_e32 v177, v177, v242
	ds_bpermute_b32 v242, v237, v177
	s_waitcnt lgkmcnt(0)
	v_add_f32_e32 v177, v177, v242
	v_rcp_f32_e32 v240, v176
	v_rcp_f32_e32 v241, v177
	s_waitcnt vmcnt(30)
	ds_write_b128 v250, v[128:131] offset:0
	ds_write_b128 v250, v[132:135] offset:4224
	ds_write_b128 v250, v[136:139] offset:16896
	ds_write_b128 v250, v[140:143] offset:21120
	s_waitcnt vmcnt(26)
	ds_write_b128 v250, v[144:147] offset:33792
	ds_write_b128 v250, v[148:151] offset:38016
	ds_write_b128 v250, v[152:155] offset:50688
	ds_write_b128 v250, v[156:159] offset:54912
	s_waitcnt vmcnt(22)
	ds_write_b128 v251, v[184:187] offset:0
	ds_write_b128 v251, v[188:191] offset:4224
	ds_write_b128 v251, v[192:195] offset:16896
	ds_write_b128 v251, v[196:199] offset:21120
	s_waitcnt vmcnt(18)
	ds_write_b128 v251, v[200:203] offset:33792
	ds_write_b128 v251, v[204:207] offset:38016
	ds_write_b128 v251, v[208:211] offset:50688
	ds_write_b128 v251, v[212:215] offset:54912
	s_waitcnt lgkmcnt(0)
	s_barrier
	s_and_b32 s0, s16, 31
	s_lshr_b32 s1, s16, 8
	s_lshl_b32 s1, s1, 5
	s_add_i32 s1, s1, s0
	s_mul_i32 s0, s1, 2731
	s_lshr_b32 s0, s0, 16
	s_mul_i32 s17, s0, 24
	s_sub_i32 s1, s1, s17
	s_bfe_u32 s17, s16, 0x30005
	s_mul_i32 s17, s17, 24
	s_add_i32 s1, s1, s17
	s_lshr_b32 s10, s1, 5
	s_sub_i32 s11, s1, 64
	s_lshr_b32 s11, s11, 4
	s_add_i32 s11, s11, 2
	s_cmp_lt_u32 s1, 64
	s_cselect_b32 s10, s10, s11
	s_lshl_b32 s11, s10, 19
	s_lshl_b32 s12, s0, 9
	s_add_u32 s11, s11, s12
	s_add_u32 s11, s11, 0x19040000
	s_add_u32 s6, s4, s11
	s_addc_u32 s7, s5, 0
	global_load_dwordx4 v[184:187], v224, s[6:7]
	s_add_u32 s6, s6, 0x8000
	s_addc_u32 s7, s7, 0
	global_load_dwordx4 v[188:191], v224, s[6:7]
	s_add_u32 s6, s6, 0x8000
	s_addc_u32 s7, s7, 0
	global_load_dwordx4 v[192:195], v224, s[6:7]
	s_add_u32 s6, s6, 0x8000
	s_addc_u32 s7, s7, 0
	global_load_dwordx4 v[196:199], v224, s[6:7]
	s_add_u32 s6, s6, 0x8000
	s_addc_u32 s7, s7, 0
	global_load_dwordx4 v[200:203], v224, s[6:7]
	s_add_u32 s6, s6, 0x8000
	s_addc_u32 s7, s7, 0
	global_load_dwordx4 v[204:207], v224, s[6:7]
	s_add_u32 s6, s6, 0x8000
	s_addc_u32 s7, s7, 0
	global_load_dwordx4 v[208:211], v224, s[6:7]
	s_add_u32 s6, s6, 0x8000
	s_addc_u32 s7, s7, 0
	global_load_dwordx4 v[212:215], v224, s[6:7]
	s_mov_b32 s18, 0
	v_mov_b32_e32 v234, v232
	v_add_u32_e32 v235, 16896, v232
	ds_read_b64 v[128:129], v234 offset:0
	ds_read_b64 v[130:131], v234 offset:32
	ds_read_b64 v[132:133], v234 offset:64
	ds_read_b64 v[134:135], v234 offset:96
	ds_read_b64 v[136:137], v234 offset:128
	ds_read_b64 v[138:139], v234 offset:160
	ds_read_b64 v[140:141], v234 offset:192
	ds_read_b64 v[142:143], v234 offset:224
	ds_read_b64 v[144:145], v234 offset:256
	ds_read_b64 v[146:147], v234 offset:288
	ds_read_b64 v[148:149], v234 offset:320
	ds_read_b64 v[150:151], v234 offset:352
